# acc zeroing via v_mov_b64, P1c row-scale prefetch before K-loop, removed redundant v_max canonicalization in P1c SiLU clamp
# speedup vs baseline: 1.0156x; 1.0114x over previous
; template <int MODE  , class Epi, class Sched>
; __device__ __forceinline__ void gemm_phase(LAS unsigned char* lds, const GemmDesc g, const Sched& S, const Epi& E) {
;     ...
; #pragma unroll
;             for (int a = 0; a < 2; ++a)
; #pragma unroll
;                 for (int b = 0; b < 2; ++b)
; #pragma unroll
;                     for (int m = 0; m < 4; ++m)
; #pragma unroll
;                         for (int n = 0; n < 2; ++n) acc[a][b][m][n] = (f32x4){0.f, 0.f, 0.f, 0.f};
;     __device__ __forceinline__ bool operator()(f32x4 (&acc)[2][2][4][2], const Unit& u, int wr, int wc, int fr, int fq) const {
;     ...
;             for (int m = 0; m < 4; ++m) { const int row = r0 + ai * HALF + m * 16; const float rq = rsc[row];
.LBB0_526:
	s_add_u32 s72, s40, 0x100
	v_mov_b32_e32 v10, 0
	s_addc_u32 s76, s41, 0
	s_mov_b32 s77, -2
	v_lshl_add_u32 v198, s73, 8, v1
	v_ashrrev_i32_e32 v199, 31, v198
	v_lshl_add_u64 v[198:199], v[198:199], 2, s[4:5]
	global_load_dword v248, v[198:199], off
	global_load_dword v249, v[198:199], off offset:64
	global_load_dword v250, v[198:199], off offset:128
	global_load_dword v251, v[198:199], off offset:192
	global_load_dword v252, v[198:199], off offset:512
	global_load_dword v253, v[198:199], off offset:576
	global_load_dword v254, v[198:199], off offset:640
	global_load_dword v255, v[198:199], off offset:704
	v_mov_b32_e32 v11, v10
	v_mov_b64_e32 v[12:13], v[10:11]
	v_mov_b64_e32 v[14:15], v[10:11]
	v_mov_b64_e32 v[16:17], v[10:11]
	v_mov_b64_e32 v[26:27], v[10:11]
	v_mov_b64_e32 v[28:29], v[10:11]
	v_mov_b64_e32 v[30:31], v[10:11]
	v_mov_b64_e32 v[32:33], v[10:11]
	v_mov_b64_e32 v[58:59], v[10:11]
	v_mov_b64_e32 v[60:61], v[10:11]
	v_mov_b64_e32 v[62:63], v[10:11]
	v_mov_b64_e32 v[64:65], v[10:11]
	v_mov_b64_e32 v[74:75], v[10:11]
	v_mov_b64_e32 v[76:77], v[10:11]
	v_mov_b64_e32 v[78:79], v[10:11]
	v_mov_b64_e32 v[80:81], v[10:11]
	v_mov_b64_e32 v[2:3], v[10:11]
	v_mov_b64_e32 v[4:5], v[10:11]
	v_mov_b64_e32 v[6:7], v[10:11]
	v_mov_b64_e32 v[8:9], v[10:11]
	v_mov_b64_e32 v[18:19], v[10:11]
	v_mov_b64_e32 v[20:21], v[10:11]
	v_mov_b64_e32 v[22:23], v[10:11]
	v_mov_b64_e32 v[24:25], v[10:11]
	v_mov_b64_e32 v[50:51], v[10:11]
	v_mov_b64_e32 v[52:53], v[10:11]
	v_mov_b64_e32 v[54:55], v[10:11]
	v_mov_b64_e32 v[56:57], v[10:11]
	v_mov_b64_e32 v[66:67], v[10:11]
	v_mov_b64_e32 v[68:69], v[10:11]
	v_mov_b64_e32 v[70:71], v[10:11]
	v_mov_b64_e32 v[72:73], v[10:11]
	v_mov_b64_e32 v[90:91], v[10:11]
	v_mov_b64_e32 v[92:93], v[10:11]
	v_mov_b64_e32 v[94:95], v[10:11]
	v_mov_b64_e32 v[96:97], v[10:11]
	v_mov_b64_e32 v[106:107], v[10:11]
	v_mov_b64_e32 v[108:109], v[10:11]
	v_mov_b64_e32 v[110:111], v[10:11]
	v_mov_b64_e32 v[112:113], v[10:11]
	v_mov_b64_e32 v[122:123], v[10:11]
	v_mov_b64_e32 v[124:125], v[10:11]
	v_mov_b64_e32 v[126:127], v[10:11]
	v_mov_b64_e32 v[128:129], v[10:11]
	v_mov_b64_e32 v[138:139], v[10:11]
	v_mov_b64_e32 v[140:141], v[10:11]
	v_mov_b64_e32 v[142:143], v[10:11]
	v_mov_b64_e32 v[144:145], v[10:11]
	v_mov_b64_e32 v[82:83], v[10:11]
	v_mov_b64_e32 v[84:85], v[10:11]
	v_mov_b64_e32 v[86:87], v[10:11]
	v_mov_b64_e32 v[88:89], v[10:11]
	v_mov_b64_e32 v[98:99], v[10:11]
	v_mov_b64_e32 v[100:101], v[10:11]
	v_mov_b64_e32 v[102:103], v[10:11]
	v_mov_b64_e32 v[104:105], v[10:11]
	v_mov_b64_e32 v[114:115], v[10:11]
	v_mov_b64_e32 v[116:117], v[10:11]
	v_mov_b64_e32 v[118:119], v[10:11]
	v_mov_b64_e32 v[120:121], v[10:11]
	v_mov_b64_e32 v[130:131], v[10:11]
	v_mov_b64_e32 v[132:133], v[10:11]
	v_mov_b64_e32 v[134:135], v[10:11]
	v_mov_b64_e32 v[136:137], v[10:11]

; __device__ __forceinline__ unsigned pk_bf16(float lo, float hi) { const f32x2_t v = {lo, hi}; return __builtin_bit_cast(unsigned, __builtin_convertvector(v, bf16x2_t)); }
; __device__ __forceinline__ float silu_f(float x) { return x * sigmoid_f(x); }
;     __device__ __forceinline__ bool operator()(f32x4 (&acc)[2][2][4][2], const Unit& u, int wr, int wc, int fr, int fq) const {
;     ...
;             for (int m = 0; m < 4; ++m) { const int row = r0 + ai * HALF + m * 16; const float rq = rsc[row];
;                 const i32x4 i00 = __builtin_bit_cast(i32x4, acc[ai][0][m][0]), i01 = __builtin_bit_cast(i32x4, acc[ai][0][m][1]), i10 = __builtin_bit_cast(i32x4, acc[ai][1][m][0]), i11 = __builtin_bit_cast(i32x4, acc[ai][1][m][1]);
;                 f32x4 a0, a1, b0, b1;
; #pragma unroll
;                 for (int j = 0; j < 4; ++j) { a0[j] = (float)i00[j] * (rq * c00[j]); a1[j] = (float)i01[j] * (rq * c01[j]); b0[j] = (float)i10[j] * (rq * c10[j]); b1[j] = (float)i11[j] * (rq * c11[j]); }
;                 if (kind == 0 || kind == 3) {
;                     if (kind == 0) {
; #pragma unroll
;                         for (int j = 0; j < 4; ++j) { a0[j] = silu_f(a0[j]); a1[j] = silu_f(a1[j]); b0[j] = silu_f(b0[j]); b1[j] = silu_f(b1[j]); } }
;                     u32x4 w; w.x = pk_bf16(a0[0], a0[1]); w.y = pk_bf16(a0[2], a0[3]); w.z = pk_bf16(a1[0], a1[1]); w.w = pk_bf16(a1[2], a1[3]);
;                     *(u32x4*)(O + (size_t)row * 1024 + c0) = w;
;                     w.x = pk_bf16(b0[0], b0[1]); w.y = pk_bf16(b0[2], b0[3]); w.z = pk_bf16(b1[0], b1[1]); w.w = pk_bf16(b1[2], b1[3]);
;                     *(u32x4*)(O + (size_t)row * 1024 + c0 + HALF) = w;
;                 } else { f32x4 v0, v1;
;                     if (kind == 1) { v0 = a0 * b0; v1 = a1 * b1; }
;                     else {
; #pragma unroll
;                         for (int j = 0; j < 4; ++j) { v0[j] = a0[j] * silu_f(b0[j]); v1[j] = a1[j] * silu_f(b1[j]); } }
.LBB0_533:
	v_lshl_add_u32 v162, s73, 8, v1
	v_ashrrev_i32_e32 v163, 31, v162
	v_lshl_add_u64 v[164:165], v[162:163], 2, s[4:5]
	v_mov_b32_e32 v154, v248
	s_mul_i32 s0, s72, 0x2200000
	s_cmp_lg_u32 s72, 3
	s_cselect_b32 s0, s0, 0xfde00000
	v_cvt_f32_i32_e32 v143, v143
	v_cvt_f32_i32_e32 v142, v142
	v_cvt_f32_i32_e32 v139, v139
	v_cvt_f32_i32_e32 v138, v138
	v_cvt_f32_i32_e32 v145, v145
	v_cvt_f32_i32_e32 v144, v144
	v_cvt_f32_i32_e32 v141, v141
	v_cvt_f32_i32_e32 v140, v140
	s_ashr_i32 s1, s0, 31
	s_lshl_b64 s[0:1], s[0:1], 1
	s_add_u32 s34, s6, s0
	s_addc_u32 s35, s7, s1
	s_cmp_lt_i32 s72, 2
	s_waitcnt vmcnt(0)
	v_pk_mul_f32 v[166:167], v[46:47], v[154:155] op_sel_hi:[1,0]
	v_pk_mul_f32 v[168:169], v[42:43], v[154:155] op_sel_hi:[1,0]
	v_pk_mul_f32 v[170:171], v[48:49], v[154:155] op_sel_hi:[1,0]
	v_pk_mul_f32 v[172:173], v[44:45], v[154:155] op_sel_hi:[1,0]
	v_pk_mul_f32 v[142:143], v[166:167], v[142:143]
	v_pk_mul_f32 v[138:139], v[168:169], v[138:139]
	v_pk_mul_f32 v[144:145], v[170:171], v[144:145]
	v_pk_mul_f32 v[140:141], v[172:173], v[140:141]
	s_cbranch_scc1 .LBB0_536
	s_mov_b64 s[44:45], -1
	s_mov_b64 s[46:47], 0
	s_cmp_lt_i32 s72, 3
	s_mov_b64 s[40:41], 0
	s_cbranch_scc0 .LBB0_537
	v_med3_f32 v168, v143, s63, v196
	v_mul_f32_e32 v168, 0xbfb8aa3b, v168
	v_med3_f32 v167, v138, s63, v196
	v_exp_f32_e32 v169, v168
	v_mul_f32_e32 v167, 0xbfb8aa3b, v167
	v_med3_f32 v168, v139, s63, v196
	v_exp_f32_e32 v167, v167
	v_mul_f32_e32 v168, 0xbfb8aa3b, v168
	v_exp_f32_e32 v170, v168
	v_add_f32_e32 v167, 1.0, v167
	v_rcp_f32_e32 v168, v167
	v_add_f32_e32 v167, 1.0, v169
	v_add_f32_e32 v169, 1.0, v170
	v_med3_f32 v171, v140, s63, v196
	v_med3_f32 v166, v142, s63, v196
	v_med3_f32 v170, v144, s63, v196
	v_mul_f32_e32 v171, 0xbfb8aa3b, v171
	v_med3_f32 v172, v145, s63, v196
	v_med3_f32 v173, v141, s63, v196
	v_mul_f32_e32 v166, 0xbfb8aa3b, v166
	v_mul_f32_e32 v170, 0xbfb8aa3b, v170
	v_exp_f32_e32 v171, v171
	v_mul_f32_e32 v172, 0xbfb8aa3b, v172
	v_mul_f32_e32 v173, 0xbfb8aa3b, v173
	v_exp_f32_e32 v166, v166
	v_exp_f32_e32 v170, v170
	v_exp_f32_e32 v172, v172
	v_exp_f32_e32 v173, v173
	v_add_f32_e32 v171, 1.0, v171
	v_add_f32_e32 v166, 1.0, v166
	v_add_f32_e32 v170, 1.0, v170
	v_rcp_f32_e32 v176, v171
	v_add_f32_e32 v171, 1.0, v172
	v_add_f32_e32 v172, 1.0, v173
	v_rcp_f32_e32 v166, v166
	v_rcp_f32_e32 v167, v167
	v_rcp_f32_e32 v169, v169
	v_rcp_f32_e32 v170, v170
	v_rcp_f32_e32 v171, v171
	v_rcp_f32_e32 v177, v172
	v_pk_mul_f32 v[174:175], v[142:143], v[166:167]
	v_pk_mul_f32 v[172:173], v[138:139], v[168:169]
	v_pk_mul_f32 v[170:171], v[144:145], v[170:171]
	v_pk_mul_f32 v[168:169], v[140:141], v[176:177]
	s_mov_b64 s[44:45], 0
	s_mov_b64 s[40:41], -1
	s_branch .LBB0_537

; __device__ __forceinline__ unsigned pk_bf16(float lo, float hi) { const f32x2_t v = {lo, hi}; return __builtin_bit_cast(unsigned, __builtin_convertvector(v, bf16x2_t)); }
; __device__ __forceinline__ float silu_f(float x) { return x * sigmoid_f(x); }
;     __device__ __forceinline__ bool operator()(f32x4 (&acc)[2][2][4][2], const Unit& u, int wr, int wc, int fr, int fq) const {
;     ...
;                 for (int j = 0; j < 4; ++j) { a0[j] = (float)i00[j] * (rq * c00[j]); a1[j] = (float)i01[j] * (rq * c01[j]); b0[j] = (float)i10[j] * (rq * c10[j]); b1[j] = (float)i11[j] * (rq * c11[j]); }
;                 if (kind == 0 || kind == 3) {
;                     if (kind == 0) {
; #pragma unroll
;                         for (int j = 0; j < 4; ++j) { a0[j] = silu_f(a0[j]); a1[j] = silu_f(a1[j]); b0[j] = silu_f(b0[j]); b1[j] = silu_f(b1[j]); } }
;                     u32x4 w; w.x = pk_bf16(a0[0], a0[1]); w.y = pk_bf16(a0[2], a0[3]); w.z = pk_bf16(a1[0], a1[1]); w.w = pk_bf16(a1[2], a1[3]);
;                     *(u32x4*)(O + (size_t)row * 1024 + c0) = w;
;                     w.x = pk_bf16(b0[0], b0[1]); w.y = pk_bf16(b0[2], b0[3]); w.z = pk_bf16(b1[0], b1[1]); w.w = pk_bf16(b1[2], b1[3]);
;                     *(u32x4*)(O + (size_t)row * 1024 + c0 + HALF) = w;
.LBB0_537:
	v_cvt_f32_i32_e32 v135, v135
	v_cvt_f32_i32_e32 v134, v134
	v_cvt_f32_i32_e32 v131, v131
	v_cvt_f32_i32_e32 v130, v130
	v_pk_mul_f32 v[166:167], v[38:39], v[154:155] op_sel_hi:[1,0]
	s_and_b64 vcc, exec, s[46:47]
	v_pk_mul_f32 v[134:135], v[166:167], v[134:135]
	v_pk_mul_f32 v[166:167], v[34:35], v[154:155] op_sel_hi:[1,0]
	s_nop 0
	v_pk_mul_f32 v[166:167], v[166:167], v[130:131]
	v_cvt_f32_i32_e32 v131, v137
	v_cvt_f32_i32_e32 v130, v136
	v_cvt_f32_i32_e32 v137, v133
	v_cvt_f32_i32_e32 v136, v132
	v_pk_mul_f32 v[132:133], v[40:41], v[154:155] op_sel_hi:[1,0]
	s_nop 0
	v_pk_mul_f32 v[132:133], v[132:133], v[130:131]
	v_pk_mul_f32 v[130:131], v[36:37], v[154:155] op_sel_hi:[1,0]
	s_nop 0
	v_pk_mul_f32 v[136:137], v[130:131], v[136:137]
	s_cbranch_vccz .LBB0_541
	s_cmp_lg_u32 s72, 1
	s_mov_b64 s[40:41], -1
	s_cbranch_scc0 .LBB0_540
	v_med3_f32 v131, v166, s63, v196
	v_mul_f32_e32 v131, 0xbfb8aa3b, v131
	v_med3_f32 v154, v142, s63, v196
	v_exp_f32_e32 v131, v131
	v_mul_f32_e32 v154, 0xbfb8aa3b, v154
	v_med3_f32 v168, v138, s63, v196
	v_exp_f32_e32 v154, v154
	v_mul_f32_e32 v168, 0xbfb8aa3b, v168
	v_exp_f32_e32 v169, v168
	v_add_f32_e32 v131, 1.0, v131
	v_rcp_f32_e32 v168, v131
	v_add_f32_e32 v131, 1.0, v154
	v_rcp_f32_e32 v170, v131
	v_add_f32_e32 v131, 1.0, v169
	v_med3_f32 v154, v135, s63, v196
	v_med3_f32 v169, v167, s63, v196
	v_mul_f32_e32 v154, 0xbfb8aa3b, v154
	v_mul_f32_e32 v169, 0xbfb8aa3b, v169
	v_exp_f32_e32 v154, v154
	v_exp_f32_e32 v169, v169
	v_rcp_f32_e32 v172, v131
	v_add_f32_e32 v131, 1.0, v154
	v_add_f32_e32 v154, 1.0, v169
	v_med3_f32 v169, v143, s63, v196
	v_mul_f32_e32 v169, 0xbfb8aa3b, v169
	v_exp_f32_e32 v171, v169
	v_med3_f32 v169, v139, s63, v196
	v_mul_f32_e32 v169, 0xbfb8aa3b, v169
	v_exp_f32_e32 v173, v169
	v_rcp_f32_e32 v169, v154
	v_add_f32_e32 v154, 1.0, v171
	v_rcp_f32_e32 v171, v154
	v_add_f32_e32 v154, 1.0, v173
	v_med3_f32 v173, v132, s63, v196
	v_mul_f32_e32 v173, 0xbfb8aa3b, v173
	v_exp_f32_e32 v174, v173
	v_med3_f32 v173, v136, s63, v196
	v_mul_f32_e32 v173, 0xbfb8aa3b, v173
	v_exp_f32_e32 v175, v173
	v_rcp_f32_e32 v173, v154
	v_add_f32_e32 v154, 1.0, v174
	v_rcp_f32_e32 v174, v154
	v_add_f32_e32 v154, 1.0, v175
	v_rcp_f32_e32 v182, v154
	v_med3_f32 v154, v144, s63, v196
	v_mul_f32_e32 v154, 0xbfb8aa3b, v154
	v_med3_f32 v175, v140, s63, v196
	v_med3_f32 v176, v133, s63, v196
	v_exp_f32_e32 v154, v154
	v_mul_f32_e32 v175, 0xbfb8aa3b, v175
	v_mul_f32_e32 v176, 0xbfb8aa3b, v176
	v_med3_f32 v130, v134, s63, v196
	v_exp_f32_e32 v175, v175
	v_exp_f32_e32 v176, v176
	v_mul_f32_e32 v130, 0xbfb8aa3b, v130
	v_exp_f32_e32 v130, v130
	v_add_f32_e32 v154, 1.0, v154
	v_rcp_f32_e32 v184, v154
	v_add_f32_e32 v154, 1.0, v175
	v_add_f32_e32 v175, 1.0, v176
	v_med3_f32 v176, v137, s63, v196
	v_add_f32_e32 v130, 1.0, v130
	v_mul_f32_e32 v176, 0xbfb8aa3b, v176
	v_rcp_f32_e32 v130, v130
	v_rcp_f32_e32 v131, v131
	v_exp_f32_e32 v178, v176
	v_rcp_f32_e32 v175, v175
	v_rcp_f32_e32 v188, v154
	v_pk_mul_f32 v[180:181], v[134:135], v[130:131]
	v_add_f32_e32 v130, 1.0, v178
	v_rcp_f32_e32 v183, v130
	v_med3_f32 v130, v145, s63, v196
	v_mul_f32_e32 v130, 0xbfb8aa3b, v130
	v_med3_f32 v131, v141, s63, v196
	v_exp_f32_e32 v130, v130
	v_mul_f32_e32 v131, 0xbfb8aa3b, v131
	v_exp_f32_e32 v131, v131
	v_pk_mul_f32 v[176:177], v[132:133], v[174:175]
	v_add_f32_e32 v130, 1.0, v130
	v_rcp_f32_e32 v185, v130
	v_add_f32_e32 v130, 1.0, v131
	v_rcp_f32_e32 v189, v130
	v_pk_mul_f32 v[178:179], v[166:167], v[168:169]
	v_pk_mul_f32 v[182:183], v[136:137], v[182:183]
	v_pk_mul_f32 v[130:131], v[142:143], v[170:171]
	v_pk_mul_f32 v[184:185], v[144:145], v[184:185]
	v_pk_mul_f32 v[186:187], v[138:139], v[172:173]
	v_pk_mul_f32 v[188:189], v[140:141], v[188:189]
	s_mov_b64 s[44:45], -1
	s_mov_b64 s[40:41], 0

; __device__ __forceinline__ unsigned pk_bf16(float lo, float hi) { const f32x2_t v = {lo, hi}; return __builtin_bit_cast(unsigned, __builtin_convertvector(v, bf16x2_t)); }
; __device__ __forceinline__ float silu_f(float x) { return x * sigmoid_f(x); }
;     __device__ __forceinline__ bool operator()(f32x4 (&acc)[2][2][4][2], const Unit& u, int wr, int wc, int fr, int fq) const {
;     ...
;             for (int m = 0; m < 4; ++m) { const int row = r0 + ai * HALF + m * 16; const float rq = rsc[row];
;                 const i32x4 i00 = __builtin_bit_cast(i32x4, acc[ai][0][m][0]), i01 = __builtin_bit_cast(i32x4, acc[ai][0][m][1]), i10 = __builtin_bit_cast(i32x4, acc[ai][1][m][0]), i11 = __builtin_bit_cast(i32x4, acc[ai][1][m][1]);
;                 f32x4 a0, a1, b0, b1;
; #pragma unroll
;                 for (int j = 0; j < 4; ++j) { a0[j] = (float)i00[j] * (rq * c00[j]); a1[j] = (float)i01[j] * (rq * c01[j]); b0[j] = (float)i10[j] * (rq * c10[j]); b1[j] = (float)i11[j] * (rq * c11[j]); }
;                 if (kind == 0 || kind == 3) {
;                     if (kind == 0) {
; #pragma unroll
;                         for (int j = 0; j < 4; ++j) { a0[j] = silu_f(a0[j]); a1[j] = silu_f(a1[j]); b0[j] = silu_f(b0[j]); b1[j] = silu_f(b1[j]); } }
;                     u32x4 w; w.x = pk_bf16(a0[0], a0[1]); w.y = pk_bf16(a0[2], a0[3]); w.z = pk_bf16(a1[0], a1[1]); w.w = pk_bf16(a1[2], a1[3]);
;                     *(u32x4*)(O + (size_t)row * 1024 + c0) = w;
;                     w.x = pk_bf16(b0[0], b0[1]); w.y = pk_bf16(b0[2], b0[3]); w.z = pk_bf16(b1[0], b1[1]); w.w = pk_bf16(b1[2], b1[3]);
;                     *(u32x4*)(O + (size_t)row * 1024 + c0 + HALF) = w;
;                 } else { f32x4 v0, v1;
;                     if (kind == 1) { v0 = a0 * b0; v1 = a1 * b1; }
;                     else {
; #pragma unroll
;                         for (int j = 0; j < 4; ++j) { v0[j] = a0[j] * silu_f(b0[j]); v1[j] = a1[j] * silu_f(b1[j]); } }
.LBB0_546:
	s_nop 1
	v_or_b32_e32 v132, 16, v162
	v_ashrrev_i32_e32 v133, 31, v132
	v_lshl_add_u64 v[134:135], v[132:133], 2, s[4:5]
	s_nop 1
	v_mov_b32_e32 v134, v249
	v_cvt_f32_i32_e32 v127, v127
	v_cvt_f32_i32_e32 v126, v126
	v_cvt_f32_i32_e32 v123, v123
	v_cvt_f32_i32_e32 v122, v122
	v_cvt_f32_i32_e32 v129, v129
	v_cvt_f32_i32_e32 v128, v128
	v_cvt_f32_i32_e32 v125, v125
	v_cvt_f32_i32_e32 v124, v124
	s_cmp_lt_i32 s72, 2
	s_nop 0
	v_pk_mul_f32 v[136:137], v[46:47], v[134:135] op_sel_hi:[1,0]
	v_pk_mul_f32 v[138:139], v[42:43], v[134:135] op_sel_hi:[1,0]
	v_pk_mul_f32 v[140:141], v[48:49], v[134:135] op_sel_hi:[1,0]
	v_pk_mul_f32 v[142:143], v[44:45], v[134:135] op_sel_hi:[1,0]
	v_pk_mul_f32 v[126:127], v[136:137], v[126:127]
	v_pk_mul_f32 v[122:123], v[138:139], v[122:123]
	v_pk_mul_f32 v[128:129], v[140:141], v[128:129]
	v_pk_mul_f32 v[124:125], v[142:143], v[124:125]
	s_cbranch_scc1 .LBB0_549
	s_mov_b64 s[40:41], -1
	s_mov_b64 s[44:45], 0
	s_cmp_lt_i32 s72, 3
	s_mov_b64 s[34:35], 0
	s_cbranch_scc0 .LBB0_550
	v_med3_f32 v135, v126, s63, v196
	v_mul_f32_e32 v135, 0xbfb8aa3b, v135
	v_med3_f32 v136, v122, s63, v196
	v_exp_f32_e32 v135, v135
	v_mul_f32_e32 v136, 0xbfb8aa3b, v136
	v_exp_f32_e32 v137, v136
	v_add_f32_e32 v135, 1.0, v135
	v_rcp_f32_e32 v136, v135
	v_add_f32_e32 v135, 1.0, v137
	v_med3_f32 v137, v127, s63, v196
	v_mul_f32_e32 v137, 0xbfb8aa3b, v137
	v_med3_f32 v138, v123, s63, v196
	v_exp_f32_e32 v137, v137
	v_mul_f32_e32 v138, 0xbfb8aa3b, v138
	v_exp_f32_e32 v138, v138
	v_rcp_f32_e32 v140, v135
	v_add_f32_e32 v135, 1.0, v137
	v_rcp_f32_e32 v137, v135
	v_add_f32_e32 v135, 1.0, v138
	v_med3_f32 v138, v128, s63, v196
	v_mul_f32_e32 v138, 0xbfb8aa3b, v138
	v_med3_f32 v139, v124, s63, v196
	v_exp_f32_e32 v138, v138
	v_mul_f32_e32 v139, 0xbfb8aa3b, v139
	v_exp_f32_e32 v139, v139
	v_rcp_f32_e32 v141, v135
	v_add_f32_e32 v135, 1.0, v138
	v_rcp_f32_e32 v138, v135
	v_add_f32_e32 v135, 1.0, v139
	v_med3_f32 v139, v129, s63, v196
	v_mul_f32_e32 v139, 0xbfb8aa3b, v139
	v_med3_f32 v142, v125, s63, v196
	v_exp_f32_e32 v139, v139
	v_mul_f32_e32 v142, 0xbfb8aa3b, v142
	v_exp_f32_e32 v142, v142
	v_rcp_f32_e32 v144, v135
	v_add_f32_e32 v135, 1.0, v139
	v_rcp_f32_e32 v139, v135
	v_add_f32_e32 v135, 1.0, v142
	v_rcp_f32_e32 v145, v135
	v_pk_mul_f32 v[142:143], v[126:127], v[136:137]
	v_pk_mul_f32 v[138:139], v[128:129], v[138:139]
	v_pk_mul_f32 v[140:141], v[122:123], v[140:141]
	v_pk_mul_f32 v[136:137], v[124:125], v[144:145]
	s_mov_b64 s[40:41], 0
	s_mov_b64 s[34:35], -1
	s_branch .LBB0_550

; __device__ __forceinline__ unsigned pk_bf16(float lo, float hi) { const f32x2_t v = {lo, hi}; return __builtin_bit_cast(unsigned, __builtin_convertvector(v, bf16x2_t)); }
; __device__ __forceinline__ float silu_f(float x) { return x * sigmoid_f(x); }
;     __device__ __forceinline__ bool operator()(f32x4 (&acc)[2][2][4][2], const Unit& u, int wr, int wc, int fr, int fq) const {
;     ...
;                 for (int j = 0; j < 4; ++j) { a0[j] = (float)i00[j] * (rq * c00[j]); a1[j] = (float)i01[j] * (rq * c01[j]); b0[j] = (float)i10[j] * (rq * c10[j]); b1[j] = (float)i11[j] * (rq * c11[j]); }
;                 if (kind == 0 || kind == 3) {
;                     if (kind == 0) {
; #pragma unroll
;                         for (int j = 0; j < 4; ++j) { a0[j] = silu_f(a0[j]); a1[j] = silu_f(a1[j]); b0[j] = silu_f(b0[j]); b1[j] = silu_f(b1[j]); } }
;                     u32x4 w; w.x = pk_bf16(a0[0], a0[1]); w.y = pk_bf16(a0[2], a0[3]); w.z = pk_bf16(a1[0], a1[1]); w.w = pk_bf16(a1[2], a1[3]);
;                     *(u32x4*)(O + (size_t)row * 1024 + c0) = w;
;                     w.x = pk_bf16(b0[0], b0[1]); w.y = pk_bf16(b0[2], b0[3]); w.z = pk_bf16(b1[0], b1[1]); w.w = pk_bf16(b1[2], b1[3]);
;                     *(u32x4*)(O + (size_t)row * 1024 + c0 + HALF) = w;
.LBB0_550:
	v_cvt_f32_i32_e32 v119, v119
	v_cvt_f32_i32_e32 v118, v118
	v_cvt_f32_i32_e32 v145, v115
	v_cvt_f32_i32_e32 v144, v114
	v_pk_mul_f32 v[114:115], v[38:39], v[134:135] op_sel_hi:[1,0]
	v_cvt_f32_i32_e32 v121, v121
	v_pk_mul_f32 v[114:115], v[114:115], v[118:119]
	v_pk_mul_f32 v[118:119], v[34:35], v[134:135] op_sel_hi:[1,0]
	v_cvt_f32_i32_e32 v120, v120
	v_pk_mul_f32 v[118:119], v[118:119], v[144:145]
	v_cvt_f32_i32_e32 v145, v117
	v_cvt_f32_i32_e32 v144, v116
	v_pk_mul_f32 v[116:117], v[40:41], v[134:135] op_sel_hi:[1,0]
	s_and_b64 vcc, exec, s[44:45]
	v_pk_mul_f32 v[116:117], v[116:117], v[120:121]
	v_pk_mul_f32 v[120:121], v[36:37], v[134:135] op_sel_hi:[1,0]
	s_nop 0
	v_pk_mul_f32 v[120:121], v[120:121], v[144:145]
	s_cbranch_vccz .LBB0_554
	s_cmp_lg_u32 s72, 1
	s_mov_b64 s[34:35], -1
	s_cbranch_scc0 .LBB0_553
	v_med3_f32 v143, v120, s63, v196
	v_med3_f32 v136, v126, s63, v196
	v_mul_f32_e32 v143, 0xbfb8aa3b, v143
	v_med3_f32 v135, v118, s63, v196
	v_mul_f32_e32 v136, 0xbfb8aa3b, v136
	v_exp_f32_e32 v143, v143
	v_mul_f32_e32 v135, 0xbfb8aa3b, v135
	v_exp_f32_e32 v137, v136
	v_exp_f32_e32 v135, v135
	v_med3_f32 v136, v122, s63, v196
	v_mul_f32_e32 v136, 0xbfb8aa3b, v136
	v_exp_f32_e32 v139, v136
	v_add_f32_e32 v143, 1.0, v143
	v_rcp_f32_e32 v168, v143
	v_add_f32_e32 v135, 1.0, v135
	v_med3_f32 v143, v128, s63, v196
	v_rcp_f32_e32 v136, v135
	v_add_f32_e32 v135, 1.0, v137
	v_mul_f32_e32 v143, 0xbfb8aa3b, v143
	v_med3_f32 v145, v117, s63, v196
	v_rcp_f32_e32 v138, v135
	v_add_f32_e32 v135, 1.0, v139
	v_exp_f32_e32 v143, v143
	v_mul_f32_e32 v145, 0xbfb8aa3b, v145
	v_med3_f32 v134, v114, s63, v196
	v_med3_f32 v137, v115, s63, v196
	v_med3_f32 v139, v119, s63, v196
	v_med3_f32 v142, v116, s63, v196
	v_exp_f32_e32 v145, v145
	v_mul_f32_e32 v134, 0xbfb8aa3b, v134
	v_mul_f32_e32 v137, 0xbfb8aa3b, v137
	v_mul_f32_e32 v139, 0xbfb8aa3b, v139
	v_mul_f32_e32 v142, 0xbfb8aa3b, v142
	v_exp_f32_e32 v134, v134
	v_exp_f32_e32 v137, v137
	v_exp_f32_e32 v139, v139
	v_exp_f32_e32 v142, v142
	v_add_f32_e32 v143, 1.0, v143
	v_med3_f32 v144, v124, s63, v196
	v_rcp_f32_e32 v172, v143
	v_add_f32_e32 v143, 1.0, v145
	v_mul_f32_e32 v144, 0xbfb8aa3b, v144
	v_med3_f32 v145, v121, s63, v196
	v_add_f32_e32 v134, 1.0, v134
	v_rcp_f32_e32 v140, v135
	v_add_f32_e32 v135, 1.0, v137
	v_add_f32_e32 v137, 1.0, v139
	v_add_f32_e32 v142, 1.0, v142
	v_exp_f32_e32 v144, v144
	v_mul_f32_e32 v145, 0xbfb8aa3b, v145
	v_rcp_f32_e32 v134, v134
	v_rcp_f32_e32 v135, v135
	v_rcp_f32_e32 v137, v137
	v_rcp_f32_e32 v142, v142
	v_rcp_f32_e32 v143, v143
	v_exp_f32_e32 v145, v145
	v_add_f32_e32 v144, 1.0, v144
	v_rcp_f32_e32 v176, v144
	v_pk_mul_f32 v[166:167], v[114:115], v[134:135]
	v_pk_mul_f32 v[134:135], v[116:117], v[142:143]
	v_add_f32_e32 v142, 1.0, v145
	v_pk_mul_f32 v[144:145], v[118:119], v[136:137]
	v_med3_f32 v136, v129, s63, v196
	v_med3_f32 v139, v127, s63, v196
	v_med3_f32 v141, v123, s63, v196
	v_mul_f32_e32 v136, 0xbfb8aa3b, v136
	v_med3_f32 v137, v125, s63, v196
	v_mul_f32_e32 v139, 0xbfb8aa3b, v139
	v_mul_f32_e32 v141, 0xbfb8aa3b, v141
	v_exp_f32_e32 v136, v136
	v_mul_f32_e32 v137, 0xbfb8aa3b, v137
	v_exp_f32_e32 v139, v139
	v_exp_f32_e32 v141, v141
	v_exp_f32_e32 v137, v137
	v_add_f32_e32 v136, 1.0, v136
	v_add_f32_e32 v139, 1.0, v139
	v_add_f32_e32 v141, 1.0, v141
	v_rcp_f32_e32 v173, v136
	v_add_f32_e32 v136, 1.0, v137
	v_rcp_f32_e32 v139, v139
	v_rcp_f32_e32 v141, v141
	v_rcp_f32_e32 v169, v142
	v_rcp_f32_e32 v177, v136
	v_pk_mul_f32 v[170:171], v[126:127], v[138:139]
	v_pk_mul_f32 v[172:173], v[128:129], v[172:173]
	v_pk_mul_f32 v[168:169], v[120:121], v[168:169]
	v_pk_mul_f32 v[174:175], v[122:123], v[140:141]
	v_pk_mul_f32 v[176:177], v[124:125], v[176:177]
	s_mov_b64 s[40:41], -1
	s_mov_b64 s[34:35], 0

; __device__ __forceinline__ unsigned pk_bf16(float lo, float hi) { const f32x2_t v = {lo, hi}; return __builtin_bit_cast(unsigned, __builtin_convertvector(v, bf16x2_t)); }
; __device__ __forceinline__ float silu_f(float x) { return x * sigmoid_f(x); }
;     __device__ __forceinline__ bool operator()(f32x4 (&acc)[2][2][4][2], const Unit& u, int wr, int wc, int fr, int fq) const {
;     ...
;             for (int m = 0; m < 4; ++m) { const int row = r0 + ai * HALF + m * 16; const float rq = rsc[row];
;                 const i32x4 i00 = __builtin_bit_cast(i32x4, acc[ai][0][m][0]), i01 = __builtin_bit_cast(i32x4, acc[ai][0][m][1]), i10 = __builtin_bit_cast(i32x4, acc[ai][1][m][0]), i11 = __builtin_bit_cast(i32x4, acc[ai][1][m][1]);
;                 f32x4 a0, a1, b0, b1;
; #pragma unroll
;                 for (int j = 0; j < 4; ++j) { a0[j] = (float)i00[j] * (rq * c00[j]); a1[j] = (float)i01[j] * (rq * c01[j]); b0[j] = (float)i10[j] * (rq * c10[j]); b1[j] = (float)i11[j] * (rq * c11[j]); }
;                 if (kind == 0 || kind == 3) {
;                     if (kind == 0) {
; #pragma unroll
;                         for (int j = 0; j < 4; ++j) { a0[j] = silu_f(a0[j]); a1[j] = silu_f(a1[j]); b0[j] = silu_f(b0[j]); b1[j] = silu_f(b1[j]); } }
;                     u32x4 w; w.x = pk_bf16(a0[0], a0[1]); w.y = pk_bf16(a0[2], a0[3]); w.z = pk_bf16(a1[0], a1[1]); w.w = pk_bf16(a1[2], a1[3]);
;                     *(u32x4*)(O + (size_t)row * 1024 + c0) = w;
;                     w.x = pk_bf16(b0[0], b0[1]); w.y = pk_bf16(b0[2], b0[3]); w.z = pk_bf16(b1[0], b1[1]); w.w = pk_bf16(b1[2], b1[3]);
;                     *(u32x4*)(O + (size_t)row * 1024 + c0 + HALF) = w;
;                 } else { f32x4 v0, v1;
;                     if (kind == 1) { v0 = a0 * b0; v1 = a1 * b1; }
;                     else {
; #pragma unroll
;                         for (int j = 0; j < 4; ++j) { v0[j] = a0[j] * silu_f(b0[j]); v1[j] = a1[j] * silu_f(b1[j]); } }
.LBB0_558:
	s_nop 1
	v_or_b32_e32 v114, 32, v162
	v_ashrrev_i32_e32 v115, 31, v114
	v_lshl_add_u64 v[116:117], v[114:115], 2, s[4:5]
	s_nop 1
	v_mov_b32_e32 v116, v250
	v_cvt_f32_i32_e32 v111, v111
	v_cvt_f32_i32_e32 v110, v110
	v_cvt_f32_i32_e32 v107, v107
	v_cvt_f32_i32_e32 v106, v106
	v_cvt_f32_i32_e32 v113, v113
	v_cvt_f32_i32_e32 v112, v112
	v_cvt_f32_i32_e32 v109, v109
	v_cvt_f32_i32_e32 v108, v108
	s_cmp_lt_i32 s72, 2
	s_nop 0
	v_pk_mul_f32 v[118:119], v[46:47], v[116:117] op_sel_hi:[1,0]
	v_pk_mul_f32 v[120:121], v[42:43], v[116:117] op_sel_hi:[1,0]
	v_pk_mul_f32 v[122:123], v[48:49], v[116:117] op_sel_hi:[1,0]
	v_pk_mul_f32 v[124:125], v[44:45], v[116:117] op_sel_hi:[1,0]
	v_pk_mul_f32 v[110:111], v[118:119], v[110:111]
	v_pk_mul_f32 v[106:107], v[120:121], v[106:107]
	v_pk_mul_f32 v[112:113], v[122:123], v[112:113]
	v_pk_mul_f32 v[108:109], v[124:125], v[108:109]
	s_cbranch_scc1 .LBB0_561
	s_mov_b64 s[40:41], -1
	s_mov_b64 s[44:45], 0
	s_cmp_lt_i32 s72, 3
	s_mov_b64 s[34:35], 0
	s_cbranch_scc0 .LBB0_562
	v_med3_f32 v117, v110, s63, v196
	v_mul_f32_e32 v117, 0xbfb8aa3b, v117
	v_med3_f32 v118, v106, s63, v196
	v_exp_f32_e32 v117, v117
	v_mul_f32_e32 v118, 0xbfb8aa3b, v118
	v_exp_f32_e32 v119, v118
	v_add_f32_e32 v117, 1.0, v117
	v_rcp_f32_e32 v118, v117
	v_add_f32_e32 v117, 1.0, v119
	v_med3_f32 v119, v111, s63, v196
	v_mul_f32_e32 v119, 0xbfb8aa3b, v119
	v_med3_f32 v120, v107, s63, v196
	v_exp_f32_e32 v119, v119
	v_mul_f32_e32 v120, 0xbfb8aa3b, v120
	v_exp_f32_e32 v120, v120
	v_rcp_f32_e32 v122, v117
	v_add_f32_e32 v117, 1.0, v119
	v_rcp_f32_e32 v119, v117
	v_add_f32_e32 v117, 1.0, v120
	v_med3_f32 v120, v112, s63, v196
	v_mul_f32_e32 v120, 0xbfb8aa3b, v120
	v_med3_f32 v121, v108, s63, v196
	v_exp_f32_e32 v120, v120
	v_mul_f32_e32 v121, 0xbfb8aa3b, v121
	v_exp_f32_e32 v121, v121
	v_rcp_f32_e32 v123, v117
	v_add_f32_e32 v117, 1.0, v120
	v_rcp_f32_e32 v120, v117
	v_add_f32_e32 v117, 1.0, v121
	v_med3_f32 v121, v113, s63, v196
	v_mul_f32_e32 v121, 0xbfb8aa3b, v121
	v_med3_f32 v124, v109, s63, v196
	v_exp_f32_e32 v121, v121
	v_mul_f32_e32 v124, 0xbfb8aa3b, v124
	v_exp_f32_e32 v124, v124
	v_rcp_f32_e32 v126, v117
	v_add_f32_e32 v117, 1.0, v121
	v_rcp_f32_e32 v121, v117
	v_add_f32_e32 v117, 1.0, v124
	v_rcp_f32_e32 v127, v117
	v_pk_mul_f32 v[124:125], v[110:111], v[118:119]
	v_pk_mul_f32 v[120:121], v[112:113], v[120:121]
	v_pk_mul_f32 v[122:123], v[106:107], v[122:123]
	v_pk_mul_f32 v[118:119], v[108:109], v[126:127]
	s_mov_b64 s[40:41], 0
	s_mov_b64 s[34:35], -1
	s_branch .LBB0_562

; __device__ __forceinline__ unsigned pk_bf16(float lo, float hi) { const f32x2_t v = {lo, hi}; return __builtin_bit_cast(unsigned, __builtin_convertvector(v, bf16x2_t)); }
; __device__ __forceinline__ float silu_f(float x) { return x * sigmoid_f(x); }
;     __device__ __forceinline__ bool operator()(f32x4 (&acc)[2][2][4][2], const Unit& u, int wr, int wc, int fr, int fq) const {
;     ...
;                 for (int j = 0; j < 4; ++j) { a0[j] = (float)i00[j] * (rq * c00[j]); a1[j] = (float)i01[j] * (rq * c01[j]); b0[j] = (float)i10[j] * (rq * c10[j]); b1[j] = (float)i11[j] * (rq * c11[j]); }
;                 if (kind == 0 || kind == 3) {
;                     if (kind == 0) {
; #pragma unroll
;                         for (int j = 0; j < 4; ++j) { a0[j] = silu_f(a0[j]); a1[j] = silu_f(a1[j]); b0[j] = silu_f(b0[j]); b1[j] = silu_f(b1[j]); } }
;                     u32x4 w; w.x = pk_bf16(a0[0], a0[1]); w.y = pk_bf16(a0[2], a0[3]); w.z = pk_bf16(a1[0], a1[1]); w.w = pk_bf16(a1[2], a1[3]);
;                     *(u32x4*)(O + (size_t)row * 1024 + c0) = w;
;                     w.x = pk_bf16(b0[0], b0[1]); w.y = pk_bf16(b0[2], b0[3]); w.z = pk_bf16(b1[0], b1[1]); w.w = pk_bf16(b1[2], b1[3]);
;                     *(u32x4*)(O + (size_t)row * 1024 + c0 + HALF) = w;
.LBB0_562:
	v_cvt_f32_i32_e32 v103, v103
	v_cvt_f32_i32_e32 v102, v102
	v_cvt_f32_i32_e32 v127, v99
	v_cvt_f32_i32_e32 v126, v98
	v_pk_mul_f32 v[98:99], v[38:39], v[116:117] op_sel_hi:[1,0]
	v_cvt_f32_i32_e32 v105, v105
	v_pk_mul_f32 v[98:99], v[98:99], v[102:103]
	v_pk_mul_f32 v[102:103], v[34:35], v[116:117] op_sel_hi:[1,0]
	v_cvt_f32_i32_e32 v104, v104
	v_pk_mul_f32 v[102:103], v[102:103], v[126:127]
	v_cvt_f32_i32_e32 v127, v101
	v_cvt_f32_i32_e32 v126, v100
	v_pk_mul_f32 v[100:101], v[40:41], v[116:117] op_sel_hi:[1,0]
	s_and_b64 vcc, exec, s[44:45]
	v_pk_mul_f32 v[100:101], v[100:101], v[104:105]
	v_pk_mul_f32 v[104:105], v[36:37], v[116:117] op_sel_hi:[1,0]
	s_nop 0
	v_pk_mul_f32 v[104:105], v[104:105], v[126:127]
	s_cbranch_vccz .LBB0_566
	s_cmp_lg_u32 s72, 1
	s_mov_b64 s[34:35], -1
	s_cbranch_scc0 .LBB0_565
	v_med3_f32 v125, v104, s63, v196
	v_med3_f32 v118, v110, s63, v196
	v_mul_f32_e32 v125, 0xbfb8aa3b, v125
	v_med3_f32 v117, v102, s63, v196
	v_mul_f32_e32 v118, 0xbfb8aa3b, v118
	v_exp_f32_e32 v125, v125
	v_mul_f32_e32 v117, 0xbfb8aa3b, v117
	v_exp_f32_e32 v119, v118
	v_exp_f32_e32 v117, v117
	v_med3_f32 v118, v106, s63, v196
	v_mul_f32_e32 v118, 0xbfb8aa3b, v118
	v_exp_f32_e32 v121, v118
	v_add_f32_e32 v125, 1.0, v125
	v_rcp_f32_e32 v132, v125
	v_add_f32_e32 v117, 1.0, v117
	v_med3_f32 v125, v112, s63, v196
	v_rcp_f32_e32 v118, v117
	v_add_f32_e32 v117, 1.0, v119
	v_mul_f32_e32 v125, 0xbfb8aa3b, v125
	v_med3_f32 v127, v101, s63, v196
	v_rcp_f32_e32 v120, v117
	v_add_f32_e32 v117, 1.0, v121
	v_exp_f32_e32 v125, v125
	v_mul_f32_e32 v127, 0xbfb8aa3b, v127
	v_med3_f32 v116, v98, s63, v196
	v_med3_f32 v119, v99, s63, v196
	v_med3_f32 v121, v103, s63, v196
	v_med3_f32 v124, v100, s63, v196
	v_exp_f32_e32 v127, v127
	v_mul_f32_e32 v116, 0xbfb8aa3b, v116
	v_mul_f32_e32 v119, 0xbfb8aa3b, v119
	v_mul_f32_e32 v121, 0xbfb8aa3b, v121
	v_mul_f32_e32 v124, 0xbfb8aa3b, v124
	v_exp_f32_e32 v116, v116
	v_exp_f32_e32 v119, v119
	v_exp_f32_e32 v121, v121
	v_exp_f32_e32 v124, v124
	v_add_f32_e32 v125, 1.0, v125
	v_med3_f32 v126, v108, s63, v196
	v_rcp_f32_e32 v136, v125
	v_add_f32_e32 v125, 1.0, v127
	v_mul_f32_e32 v126, 0xbfb8aa3b, v126
	v_med3_f32 v127, v105, s63, v196
	v_add_f32_e32 v116, 1.0, v116
	v_rcp_f32_e32 v122, v117
	v_add_f32_e32 v117, 1.0, v119
	v_add_f32_e32 v119, 1.0, v121
	v_add_f32_e32 v124, 1.0, v124
	v_exp_f32_e32 v126, v126
	v_mul_f32_e32 v127, 0xbfb8aa3b, v127
	v_rcp_f32_e32 v116, v116
	v_rcp_f32_e32 v117, v117
	v_rcp_f32_e32 v119, v119
	v_rcp_f32_e32 v124, v124
	v_rcp_f32_e32 v125, v125
	v_exp_f32_e32 v127, v127
	v_add_f32_e32 v126, 1.0, v126
	v_rcp_f32_e32 v140, v126
	v_pk_mul_f32 v[128:129], v[98:99], v[116:117]
	v_pk_mul_f32 v[116:117], v[100:101], v[124:125]
	v_add_f32_e32 v124, 1.0, v127
	v_pk_mul_f32 v[126:127], v[102:103], v[118:119]
	v_med3_f32 v118, v113, s63, v196
	v_med3_f32 v121, v111, s63, v196
	v_med3_f32 v123, v107, s63, v196
	v_mul_f32_e32 v118, 0xbfb8aa3b, v118
	v_med3_f32 v119, v109, s63, v196
	v_mul_f32_e32 v121, 0xbfb8aa3b, v121
	v_mul_f32_e32 v123, 0xbfb8aa3b, v123
	v_exp_f32_e32 v118, v118
	v_mul_f32_e32 v119, 0xbfb8aa3b, v119
	v_exp_f32_e32 v121, v121
	v_exp_f32_e32 v123, v123
	v_exp_f32_e32 v119, v119
	v_add_f32_e32 v118, 1.0, v118
	v_add_f32_e32 v121, 1.0, v121
	v_add_f32_e32 v123, 1.0, v123
	v_rcp_f32_e32 v137, v118
	v_add_f32_e32 v118, 1.0, v119
	v_rcp_f32_e32 v121, v121
	v_rcp_f32_e32 v123, v123
	v_rcp_f32_e32 v133, v124
	v_rcp_f32_e32 v141, v118
	v_pk_mul_f32 v[134:135], v[110:111], v[120:121]
	v_pk_mul_f32 v[136:137], v[112:113], v[136:137]
	v_pk_mul_f32 v[132:133], v[104:105], v[132:133]
	v_pk_mul_f32 v[138:139], v[106:107], v[122:123]
	v_pk_mul_f32 v[140:141], v[108:109], v[140:141]
	s_mov_b64 s[40:41], -1
	s_mov_b64 s[34:35], 0

; __device__ __forceinline__ unsigned pk_bf16(float lo, float hi) { const f32x2_t v = {lo, hi}; return __builtin_bit_cast(unsigned, __builtin_convertvector(v, bf16x2_t)); }
; __device__ __forceinline__ float silu_f(float x) { return x * sigmoid_f(x); }
;     __device__ __forceinline__ bool operator()(f32x4 (&acc)[2][2][4][2], const Unit& u, int wr, int wc, int fr, int fq) const {
;     ...
;             for (int m = 0; m < 4; ++m) { const int row = r0 + ai * HALF + m * 16; const float rq = rsc[row];
;                 const i32x4 i00 = __builtin_bit_cast(i32x4, acc[ai][0][m][0]), i01 = __builtin_bit_cast(i32x4, acc[ai][0][m][1]), i10 = __builtin_bit_cast(i32x4, acc[ai][1][m][0]), i11 = __builtin_bit_cast(i32x4, acc[ai][1][m][1]);
;                 f32x4 a0, a1, b0, b1;
; #pragma unroll
;                 for (int j = 0; j < 4; ++j) { a0[j] = (float)i00[j] * (rq * c00[j]); a1[j] = (float)i01[j] * (rq * c01[j]); b0[j] = (float)i10[j] * (rq * c10[j]); b1[j] = (float)i11[j] * (rq * c11[j]); }
;                 if (kind == 0 || kind == 3) {
;                     if (kind == 0) {
; #pragma unroll
;                         for (int j = 0; j < 4; ++j) { a0[j] = silu_f(a0[j]); a1[j] = silu_f(a1[j]); b0[j] = silu_f(b0[j]); b1[j] = silu_f(b1[j]); } }
;                     u32x4 w; w.x = pk_bf16(a0[0], a0[1]); w.y = pk_bf16(a0[2], a0[3]); w.z = pk_bf16(a1[0], a1[1]); w.w = pk_bf16(a1[2], a1[3]);
;                     *(u32x4*)(O + (size_t)row * 1024 + c0) = w;
;                     w.x = pk_bf16(b0[0], b0[1]); w.y = pk_bf16(b0[2], b0[3]); w.z = pk_bf16(b1[0], b1[1]); w.w = pk_bf16(b1[2], b1[3]);
;                     *(u32x4*)(O + (size_t)row * 1024 + c0 + HALF) = w;
;                 } else { f32x4 v0, v1;
;                     if (kind == 1) { v0 = a0 * b0; v1 = a1 * b1; }
;                     else {
; #pragma unroll
;                         for (int j = 0; j < 4; ++j) { v0[j] = a0[j] * silu_f(b0[j]); v1[j] = a1[j] * silu_f(b1[j]); } }
.LBB0_570:
	s_nop 1
	v_or_b32_e32 v98, 48, v162
	v_ashrrev_i32_e32 v99, 31, v98
	v_lshl_add_u64 v[100:101], v[98:99], 2, s[4:5]
	s_nop 1
	v_mov_b32_e32 v100, v251
	v_cvt_f32_i32_e32 v95, v95
	v_cvt_f32_i32_e32 v94, v94
	v_cvt_f32_i32_e32 v91, v91
	v_cvt_f32_i32_e32 v90, v90
	v_cvt_f32_i32_e32 v97, v97
	v_cvt_f32_i32_e32 v96, v96
	v_cvt_f32_i32_e32 v93, v93
	v_cvt_f32_i32_e32 v92, v92
	s_cmp_lt_i32 s72, 2
	s_nop 0
	v_pk_mul_f32 v[102:103], v[46:47], v[100:101] op_sel_hi:[1,0]
	v_pk_mul_f32 v[104:105], v[42:43], v[100:101] op_sel_hi:[1,0]
	v_pk_mul_f32 v[106:107], v[48:49], v[100:101] op_sel_hi:[1,0]
	v_pk_mul_f32 v[108:109], v[44:45], v[100:101] op_sel_hi:[1,0]
	v_pk_mul_f32 v[94:95], v[102:103], v[94:95]
	v_pk_mul_f32 v[90:91], v[104:105], v[90:91]
	v_pk_mul_f32 v[96:97], v[106:107], v[96:97]
	v_pk_mul_f32 v[92:93], v[108:109], v[92:93]
	s_cbranch_scc1 .LBB0_573
	s_mov_b64 s[40:41], -1
	s_mov_b64 s[44:45], 0
	s_cmp_lt_i32 s72, 3
	s_mov_b64 s[34:35], 0
	s_cbranch_scc0 .LBB0_574
	v_med3_f32 v101, v94, s63, v196
	v_mul_f32_e32 v101, 0xbfb8aa3b, v101
	v_med3_f32 v102, v90, s63, v196
	v_exp_f32_e32 v101, v101
	v_mul_f32_e32 v102, 0xbfb8aa3b, v102
	v_exp_f32_e32 v103, v102
	v_add_f32_e32 v101, 1.0, v101
	v_rcp_f32_e32 v102, v101
	v_add_f32_e32 v101, 1.0, v103
	v_med3_f32 v103, v95, s63, v196
	v_mul_f32_e32 v103, 0xbfb8aa3b, v103
	v_med3_f32 v104, v91, s63, v196
	v_exp_f32_e32 v103, v103
	v_mul_f32_e32 v104, 0xbfb8aa3b, v104
	v_exp_f32_e32 v104, v104
	v_rcp_f32_e32 v106, v101
	v_add_f32_e32 v101, 1.0, v103
	v_rcp_f32_e32 v103, v101
	v_add_f32_e32 v101, 1.0, v104
	v_med3_f32 v104, v96, s63, v196
	v_mul_f32_e32 v104, 0xbfb8aa3b, v104
	v_med3_f32 v105, v92, s63, v196
	v_exp_f32_e32 v104, v104
	v_mul_f32_e32 v105, 0xbfb8aa3b, v105
	v_exp_f32_e32 v105, v105
	v_rcp_f32_e32 v107, v101
	v_add_f32_e32 v101, 1.0, v104
	v_rcp_f32_e32 v104, v101
	v_add_f32_e32 v101, 1.0, v105
	v_med3_f32 v105, v97, s63, v196
	v_mul_f32_e32 v105, 0xbfb8aa3b, v105
	v_med3_f32 v108, v93, s63, v196
	v_exp_f32_e32 v105, v105
	v_mul_f32_e32 v108, 0xbfb8aa3b, v108
	v_exp_f32_e32 v108, v108
	v_rcp_f32_e32 v110, v101
	v_add_f32_e32 v101, 1.0, v105
	v_rcp_f32_e32 v105, v101
	v_add_f32_e32 v101, 1.0, v108
	v_rcp_f32_e32 v111, v101
	v_pk_mul_f32 v[108:109], v[94:95], v[102:103]
	v_pk_mul_f32 v[104:105], v[96:97], v[104:105]
	v_pk_mul_f32 v[106:107], v[90:91], v[106:107]
	v_pk_mul_f32 v[102:103], v[92:93], v[110:111]
	s_mov_b64 s[40:41], 0
	s_mov_b64 s[34:35], -1
	s_branch .LBB0_574

; __device__ __forceinline__ unsigned pk_bf16(float lo, float hi) { const f32x2_t v = {lo, hi}; return __builtin_bit_cast(unsigned, __builtin_convertvector(v, bf16x2_t)); }
; __device__ __forceinline__ float silu_f(float x) { return x * sigmoid_f(x); }
;     __device__ __forceinline__ bool operator()(f32x4 (&acc)[2][2][4][2], const Unit& u, int wr, int wc, int fr, int fq) const {
;     ...
;                 for (int j = 0; j < 4; ++j) { a0[j] = (float)i00[j] * (rq * c00[j]); a1[j] = (float)i01[j] * (rq * c01[j]); b0[j] = (float)i10[j] * (rq * c10[j]); b1[j] = (float)i11[j] * (rq * c11[j]); }
;                 if (kind == 0 || kind == 3) {
;                     if (kind == 0) {
; #pragma unroll
;                         for (int j = 0; j < 4; ++j) { a0[j] = silu_f(a0[j]); a1[j] = silu_f(a1[j]); b0[j] = silu_f(b0[j]); b1[j] = silu_f(b1[j]); } }
;                     u32x4 w; w.x = pk_bf16(a0[0], a0[1]); w.y = pk_bf16(a0[2], a0[3]); w.z = pk_bf16(a1[0], a1[1]); w.w = pk_bf16(a1[2], a1[3]);
;                     *(u32x4*)(O + (size_t)row * 1024 + c0) = w;
;                     w.x = pk_bf16(b0[0], b0[1]); w.y = pk_bf16(b0[2], b0[3]); w.z = pk_bf16(b1[0], b1[1]); w.w = pk_bf16(b1[2], b1[3]);
;                     *(u32x4*)(O + (size_t)row * 1024 + c0 + HALF) = w;
.LBB0_574:
	v_cvt_f32_i32_e32 v87, v87
	v_cvt_f32_i32_e32 v86, v86
	v_cvt_f32_i32_e32 v111, v83
	v_cvt_f32_i32_e32 v110, v82
	v_pk_mul_f32 v[82:83], v[38:39], v[100:101] op_sel_hi:[1,0]
	v_cvt_f32_i32_e32 v89, v89
	v_pk_mul_f32 v[82:83], v[82:83], v[86:87]
	v_pk_mul_f32 v[86:87], v[34:35], v[100:101] op_sel_hi:[1,0]
	v_cvt_f32_i32_e32 v88, v88
	v_pk_mul_f32 v[86:87], v[86:87], v[110:111]
	v_cvt_f32_i32_e32 v111, v85
	v_cvt_f32_i32_e32 v110, v84
	v_pk_mul_f32 v[84:85], v[40:41], v[100:101] op_sel_hi:[1,0]
	s_and_b64 vcc, exec, s[44:45]
	v_pk_mul_f32 v[84:85], v[84:85], v[88:89]
	v_pk_mul_f32 v[88:89], v[36:37], v[100:101] op_sel_hi:[1,0]
	s_nop 0
	v_pk_mul_f32 v[88:89], v[88:89], v[110:111]
	s_cbranch_vccz .LBB0_578
	s_cmp_lg_u32 s72, 1
	s_mov_b64 s[34:35], -1
	s_cbranch_scc0 .LBB0_577
	v_med3_f32 v109, v88, s63, v196
	v_med3_f32 v102, v94, s63, v196
	v_mul_f32_e32 v109, 0xbfb8aa3b, v109
	v_med3_f32 v101, v86, s63, v196
	v_mul_f32_e32 v102, 0xbfb8aa3b, v102
	v_exp_f32_e32 v109, v109
	v_mul_f32_e32 v101, 0xbfb8aa3b, v101
	v_exp_f32_e32 v103, v102
	v_exp_f32_e32 v101, v101
	v_med3_f32 v102, v90, s63, v196
	v_mul_f32_e32 v102, 0xbfb8aa3b, v102
	v_exp_f32_e32 v105, v102
	v_add_f32_e32 v109, 1.0, v109
	v_rcp_f32_e32 v114, v109
	v_add_f32_e32 v101, 1.0, v101
	v_med3_f32 v109, v96, s63, v196
	v_rcp_f32_e32 v102, v101
	v_add_f32_e32 v101, 1.0, v103
	v_mul_f32_e32 v109, 0xbfb8aa3b, v109
	v_med3_f32 v111, v85, s63, v196
	v_rcp_f32_e32 v104, v101
	v_add_f32_e32 v101, 1.0, v105
	v_exp_f32_e32 v109, v109
	v_mul_f32_e32 v111, 0xbfb8aa3b, v111
	v_med3_f32 v100, v82, s63, v196
	v_med3_f32 v103, v83, s63, v196
	v_med3_f32 v105, v87, s63, v196
	v_med3_f32 v108, v84, s63, v196
	v_exp_f32_e32 v111, v111
	v_mul_f32_e32 v100, 0xbfb8aa3b, v100
	v_mul_f32_e32 v103, 0xbfb8aa3b, v103
	v_mul_f32_e32 v105, 0xbfb8aa3b, v105
	v_mul_f32_e32 v108, 0xbfb8aa3b, v108
	v_exp_f32_e32 v100, v100
	v_exp_f32_e32 v103, v103
	v_exp_f32_e32 v105, v105
	v_exp_f32_e32 v108, v108
	v_add_f32_e32 v109, 1.0, v109
	v_med3_f32 v110, v92, s63, v196
	v_rcp_f32_e32 v118, v109
	v_add_f32_e32 v109, 1.0, v111
	v_mul_f32_e32 v110, 0xbfb8aa3b, v110
	v_med3_f32 v111, v89, s63, v196
	v_add_f32_e32 v100, 1.0, v100
	v_rcp_f32_e32 v106, v101
	v_add_f32_e32 v101, 1.0, v103
	v_add_f32_e32 v103, 1.0, v105
	v_add_f32_e32 v108, 1.0, v108
	v_exp_f32_e32 v110, v110
	v_mul_f32_e32 v111, 0xbfb8aa3b, v111
	v_rcp_f32_e32 v100, v100
	v_rcp_f32_e32 v101, v101
	v_rcp_f32_e32 v103, v103
	v_rcp_f32_e32 v108, v108
	v_rcp_f32_e32 v109, v109
	v_exp_f32_e32 v111, v111
	v_add_f32_e32 v110, 1.0, v110
	v_rcp_f32_e32 v122, v110
	v_pk_mul_f32 v[112:113], v[82:83], v[100:101]
	v_pk_mul_f32 v[100:101], v[84:85], v[108:109]
	v_add_f32_e32 v108, 1.0, v111
	v_pk_mul_f32 v[110:111], v[86:87], v[102:103]
	v_med3_f32 v102, v97, s63, v196
	v_med3_f32 v105, v95, s63, v196
	v_med3_f32 v107, v91, s63, v196
	v_mul_f32_e32 v102, 0xbfb8aa3b, v102
	v_med3_f32 v103, v93, s63, v196
	v_mul_f32_e32 v105, 0xbfb8aa3b, v105
	v_mul_f32_e32 v107, 0xbfb8aa3b, v107
	v_exp_f32_e32 v102, v102
	v_mul_f32_e32 v103, 0xbfb8aa3b, v103
	v_exp_f32_e32 v105, v105
	v_exp_f32_e32 v107, v107
	v_exp_f32_e32 v103, v103
	v_add_f32_e32 v102, 1.0, v102
	v_add_f32_e32 v105, 1.0, v105
	v_add_f32_e32 v107, 1.0, v107
	v_rcp_f32_e32 v119, v102
	v_add_f32_e32 v102, 1.0, v103
	v_rcp_f32_e32 v105, v105
	v_rcp_f32_e32 v107, v107
	v_rcp_f32_e32 v115, v108
	v_rcp_f32_e32 v123, v102
	v_pk_mul_f32 v[116:117], v[94:95], v[104:105]
	v_pk_mul_f32 v[118:119], v[96:97], v[118:119]
	v_pk_mul_f32 v[114:115], v[88:89], v[114:115]
	v_pk_mul_f32 v[120:121], v[90:91], v[106:107]
	v_pk_mul_f32 v[122:123], v[92:93], v[122:123]
	s_mov_b64 s[40:41], -1
	s_mov_b64 s[34:35], 0

; __device__ __forceinline__ unsigned pk_bf16(float lo, float hi) { const f32x2_t v = {lo, hi}; return __builtin_bit_cast(unsigned, __builtin_convertvector(v, bf16x2_t)); }
; __device__ __forceinline__ float silu_f(float x) { return x * sigmoid_f(x); }
;     __device__ __forceinline__ bool operator()(f32x4 (&acc)[2][2][4][2], const Unit& u, int wr, int wc, int fr, int fq) const {
;     ...
;             for (int m = 0; m < 4; ++m) { const int row = r0 + ai * HALF + m * 16; const float rq = rsc[row];
;                 const i32x4 i00 = __builtin_bit_cast(i32x4, acc[ai][0][m][0]), i01 = __builtin_bit_cast(i32x4, acc[ai][0][m][1]), i10 = __builtin_bit_cast(i32x4, acc[ai][1][m][0]), i11 = __builtin_bit_cast(i32x4, acc[ai][1][m][1]);
;                 f32x4 a0, a1, b0, b1;
; #pragma unroll
;                 for (int j = 0; j < 4; ++j) { a0[j] = (float)i00[j] * (rq * c00[j]); a1[j] = (float)i01[j] * (rq * c01[j]); b0[j] = (float)i10[j] * (rq * c10[j]); b1[j] = (float)i11[j] * (rq * c11[j]); }
;                 if (kind == 0 || kind == 3) {
;                     if (kind == 0) {
; #pragma unroll
;                         for (int j = 0; j < 4; ++j) { a0[j] = silu_f(a0[j]); a1[j] = silu_f(a1[j]); b0[j] = silu_f(b0[j]); b1[j] = silu_f(b1[j]); } }
;                     u32x4 w; w.x = pk_bf16(a0[0], a0[1]); w.y = pk_bf16(a0[2], a0[3]); w.z = pk_bf16(a1[0], a1[1]); w.w = pk_bf16(a1[2], a1[3]);
;                     *(u32x4*)(O + (size_t)row * 1024 + c0) = w;
;                     w.x = pk_bf16(b0[0], b0[1]); w.y = pk_bf16(b0[2], b0[3]); w.z = pk_bf16(b1[0], b1[1]); w.w = pk_bf16(b1[2], b1[3]);
;                     *(u32x4*)(O + (size_t)row * 1024 + c0 + HALF) = w;
;                 } else { f32x4 v0, v1;
;                     if (kind == 1) { v0 = a0 * b0; v1 = a1 * b1; }
;                     else {
; #pragma unroll
;                         for (int j = 0; j < 4; ++j) { v0[j] = a0[j] * silu_f(b0[j]); v1[j] = a1[j] * silu_f(b1[j]); } }
.LBB0_582:
	s_nop 1
	v_mov_b32_e32 v82, v252
	v_cvt_f32_i32_e32 v79, v79
	v_cvt_f32_i32_e32 v78, v78
	v_cvt_f32_i32_e32 v75, v75
	v_cvt_f32_i32_e32 v74, v74
	v_cvt_f32_i32_e32 v81, v81
	v_cvt_f32_i32_e32 v80, v80
	v_cvt_f32_i32_e32 v77, v77
	v_cvt_f32_i32_e32 v76, v76
	s_cmp_lt_i32 s72, 2
	s_nop 0
	v_pk_mul_f32 v[84:85], v[46:47], v[82:83] op_sel_hi:[1,0]
	v_pk_mul_f32 v[86:87], v[42:43], v[82:83] op_sel_hi:[1,0]
	v_pk_mul_f32 v[88:89], v[48:49], v[82:83] op_sel_hi:[1,0]
	v_pk_mul_f32 v[90:91], v[44:45], v[82:83] op_sel_hi:[1,0]
	v_pk_mul_f32 v[78:79], v[84:85], v[78:79]
	v_pk_mul_f32 v[74:75], v[86:87], v[74:75]
	v_pk_mul_f32 v[80:81], v[88:89], v[80:81]
	v_pk_mul_f32 v[76:77], v[90:91], v[76:77]
	s_cbranch_scc1 .LBB0_585
	s_mov_b64 s[40:41], -1
	s_mov_b64 s[44:45], 0
	s_cmp_lt_i32 s72, 3
	s_mov_b64 s[34:35], 0
	s_cbranch_scc0 .LBB0_586
	v_med3_f32 v83, v78, s63, v196
	v_mul_f32_e32 v83, 0xbfb8aa3b, v83
	v_med3_f32 v84, v74, s63, v196
	v_exp_f32_e32 v83, v83
	v_mul_f32_e32 v84, 0xbfb8aa3b, v84
	v_exp_f32_e32 v85, v84
	v_add_f32_e32 v83, 1.0, v83
	v_rcp_f32_e32 v84, v83
	v_add_f32_e32 v83, 1.0, v85
	v_med3_f32 v85, v79, s63, v196
	v_mul_f32_e32 v85, 0xbfb8aa3b, v85
	v_med3_f32 v86, v75, s63, v196
	v_exp_f32_e32 v85, v85
	v_mul_f32_e32 v86, 0xbfb8aa3b, v86
	v_exp_f32_e32 v86, v86
	v_rcp_f32_e32 v88, v83
	v_add_f32_e32 v83, 1.0, v85
	v_rcp_f32_e32 v85, v83
	v_add_f32_e32 v83, 1.0, v86
	v_med3_f32 v86, v80, s63, v196
	v_mul_f32_e32 v86, 0xbfb8aa3b, v86
	v_med3_f32 v87, v76, s63, v196
	v_exp_f32_e32 v86, v86
	v_mul_f32_e32 v87, 0xbfb8aa3b, v87
	v_exp_f32_e32 v87, v87
	v_rcp_f32_e32 v89, v83
	v_add_f32_e32 v83, 1.0, v86
	v_rcp_f32_e32 v86, v83
	v_add_f32_e32 v83, 1.0, v87
	v_med3_f32 v87, v81, s63, v196
	v_mul_f32_e32 v87, 0xbfb8aa3b, v87
	v_med3_f32 v90, v77, s63, v196
	v_exp_f32_e32 v87, v87
	v_mul_f32_e32 v90, 0xbfb8aa3b, v90
	v_exp_f32_e32 v90, v90
	v_rcp_f32_e32 v92, v83
	v_add_f32_e32 v83, 1.0, v87
	v_rcp_f32_e32 v87, v83
	v_add_f32_e32 v83, 1.0, v90
	v_rcp_f32_e32 v93, v83
	v_pk_mul_f32 v[90:91], v[78:79], v[84:85]
	v_pk_mul_f32 v[86:87], v[80:81], v[86:87]
	v_pk_mul_f32 v[88:89], v[74:75], v[88:89]
	v_pk_mul_f32 v[84:85], v[76:77], v[92:93]
	s_mov_b64 s[40:41], 0
	s_mov_b64 s[34:35], -1
	s_branch .LBB0_586

; __device__ __forceinline__ unsigned pk_bf16(float lo, float hi) { const f32x2_t v = {lo, hi}; return __builtin_bit_cast(unsigned, __builtin_convertvector(v, bf16x2_t)); }
; __device__ __forceinline__ float silu_f(float x) { return x * sigmoid_f(x); }
;     __device__ __forceinline__ bool operator()(f32x4 (&acc)[2][2][4][2], const Unit& u, int wr, int wc, int fr, int fq) const {
;     ...
;                 for (int j = 0; j < 4; ++j) { a0[j] = (float)i00[j] * (rq * c00[j]); a1[j] = (float)i01[j] * (rq * c01[j]); b0[j] = (float)i10[j] * (rq * c10[j]); b1[j] = (float)i11[j] * (rq * c11[j]); }
;                 if (kind == 0 || kind == 3) {
;                     if (kind == 0) {
; #pragma unroll
;                         for (int j = 0; j < 4; ++j) { a0[j] = silu_f(a0[j]); a1[j] = silu_f(a1[j]); b0[j] = silu_f(b0[j]); b1[j] = silu_f(b1[j]); } }
;                     u32x4 w; w.x = pk_bf16(a0[0], a0[1]); w.y = pk_bf16(a0[2], a0[3]); w.z = pk_bf16(a1[0], a1[1]); w.w = pk_bf16(a1[2], a1[3]);
;                     *(u32x4*)(O + (size_t)row * 1024 + c0) = w;
;                     w.x = pk_bf16(b0[0], b0[1]); w.y = pk_bf16(b0[2], b0[3]); w.z = pk_bf16(b1[0], b1[1]); w.w = pk_bf16(b1[2], b1[3]);
;                     *(u32x4*)(O + (size_t)row * 1024 + c0 + HALF) = w;
.LBB0_586:
	v_cvt_f32_i32_e32 v71, v71
	v_cvt_f32_i32_e32 v70, v70
	v_cvt_f32_i32_e32 v93, v67
	v_cvt_f32_i32_e32 v92, v66
	v_pk_mul_f32 v[66:67], v[38:39], v[82:83] op_sel_hi:[1,0]
	v_cvt_f32_i32_e32 v73, v73
	v_pk_mul_f32 v[66:67], v[66:67], v[70:71]
	v_pk_mul_f32 v[70:71], v[34:35], v[82:83] op_sel_hi:[1,0]
	v_cvt_f32_i32_e32 v72, v72
	v_pk_mul_f32 v[70:71], v[70:71], v[92:93]
	v_cvt_f32_i32_e32 v93, v69
	v_cvt_f32_i32_e32 v92, v68
	v_pk_mul_f32 v[68:69], v[40:41], v[82:83] op_sel_hi:[1,0]
	s_and_b64 vcc, exec, s[44:45]
	v_pk_mul_f32 v[68:69], v[68:69], v[72:73]
	v_pk_mul_f32 v[72:73], v[36:37], v[82:83] op_sel_hi:[1,0]
	s_nop 0
	v_pk_mul_f32 v[72:73], v[72:73], v[92:93]
	s_cbranch_vccz .LBB0_590
	s_cmp_lg_u32 s72, 1
	s_mov_b64 s[34:35], -1
	s_cbranch_scc0 .LBB0_589
	v_med3_f32 v91, v72, s63, v196
	v_med3_f32 v84, v78, s63, v196
	v_mul_f32_e32 v91, 0xbfb8aa3b, v91
	v_med3_f32 v83, v70, s63, v196
	v_mul_f32_e32 v84, 0xbfb8aa3b, v84
	v_exp_f32_e32 v91, v91
	v_mul_f32_e32 v83, 0xbfb8aa3b, v83
	v_exp_f32_e32 v85, v84
	v_exp_f32_e32 v83, v83
	v_med3_f32 v84, v74, s63, v196
	v_mul_f32_e32 v84, 0xbfb8aa3b, v84
	v_exp_f32_e32 v87, v84
	v_add_f32_e32 v91, 1.0, v91
	v_rcp_f32_e32 v96, v91
	v_add_f32_e32 v83, 1.0, v83
	v_med3_f32 v91, v80, s63, v196
	v_rcp_f32_e32 v84, v83
	v_add_f32_e32 v83, 1.0, v85
	v_mul_f32_e32 v91, 0xbfb8aa3b, v91
	v_med3_f32 v93, v69, s63, v196
	v_rcp_f32_e32 v86, v83
	v_add_f32_e32 v83, 1.0, v87
	v_exp_f32_e32 v91, v91
	v_mul_f32_e32 v93, 0xbfb8aa3b, v93
	v_med3_f32 v82, v66, s63, v196
	v_med3_f32 v85, v67, s63, v196
	v_med3_f32 v87, v71, s63, v196
	v_med3_f32 v90, v68, s63, v196
	v_exp_f32_e32 v93, v93
	v_mul_f32_e32 v82, 0xbfb8aa3b, v82
	v_mul_f32_e32 v85, 0xbfb8aa3b, v85
	v_mul_f32_e32 v87, 0xbfb8aa3b, v87
	v_mul_f32_e32 v90, 0xbfb8aa3b, v90
	v_exp_f32_e32 v82, v82
	v_exp_f32_e32 v85, v85
	v_exp_f32_e32 v87, v87
	v_exp_f32_e32 v90, v90
	v_add_f32_e32 v91, 1.0, v91
	v_med3_f32 v92, v76, s63, v196
	v_rcp_f32_e32 v100, v91
	v_add_f32_e32 v91, 1.0, v93
	v_mul_f32_e32 v92, 0xbfb8aa3b, v92
	v_med3_f32 v93, v73, s63, v196
	v_add_f32_e32 v82, 1.0, v82
	v_rcp_f32_e32 v88, v83
	v_add_f32_e32 v83, 1.0, v85
	v_add_f32_e32 v85, 1.0, v87
	v_add_f32_e32 v90, 1.0, v90
	v_exp_f32_e32 v92, v92
	v_mul_f32_e32 v93, 0xbfb8aa3b, v93
	v_rcp_f32_e32 v82, v82
	v_rcp_f32_e32 v83, v83
	v_rcp_f32_e32 v85, v85
	v_rcp_f32_e32 v90, v90
	v_rcp_f32_e32 v91, v91
	v_exp_f32_e32 v93, v93
	v_add_f32_e32 v92, 1.0, v92
	v_rcp_f32_e32 v104, v92
	v_pk_mul_f32 v[94:95], v[66:67], v[82:83]
	v_pk_mul_f32 v[82:83], v[68:69], v[90:91]
	v_add_f32_e32 v90, 1.0, v93
	v_pk_mul_f32 v[92:93], v[70:71], v[84:85]
	v_med3_f32 v84, v81, s63, v196
	v_med3_f32 v87, v79, s63, v196
	v_med3_f32 v89, v75, s63, v196
	v_mul_f32_e32 v84, 0xbfb8aa3b, v84
	v_med3_f32 v85, v77, s63, v196
	v_mul_f32_e32 v87, 0xbfb8aa3b, v87
	v_mul_f32_e32 v89, 0xbfb8aa3b, v89
	v_exp_f32_e32 v84, v84
	v_mul_f32_e32 v85, 0xbfb8aa3b, v85
	v_exp_f32_e32 v87, v87
	v_exp_f32_e32 v89, v89
	v_exp_f32_e32 v85, v85
	v_add_f32_e32 v84, 1.0, v84
	v_add_f32_e32 v87, 1.0, v87
	v_add_f32_e32 v89, 1.0, v89
	v_rcp_f32_e32 v101, v84
	v_add_f32_e32 v84, 1.0, v85
	v_rcp_f32_e32 v87, v87
	v_rcp_f32_e32 v89, v89
	v_rcp_f32_e32 v97, v90
	v_rcp_f32_e32 v105, v84
	v_pk_mul_f32 v[98:99], v[78:79], v[86:87]
	v_pk_mul_f32 v[100:101], v[80:81], v[100:101]
	v_pk_mul_f32 v[96:97], v[72:73], v[96:97]
	v_pk_mul_f32 v[102:103], v[74:75], v[88:89]
	v_pk_mul_f32 v[104:105], v[76:77], v[104:105]
	s_mov_b64 s[40:41], -1
	s_mov_b64 s[34:35], 0

; __device__ __forceinline__ unsigned pk_bf16(float lo, float hi) { const f32x2_t v = {lo, hi}; return __builtin_bit_cast(unsigned, __builtin_convertvector(v, bf16x2_t)); }
; __device__ __forceinline__ float silu_f(float x) { return x * sigmoid_f(x); }
;     __device__ __forceinline__ bool operator()(f32x4 (&acc)[2][2][4][2], const Unit& u, int wr, int wc, int fr, int fq) const {
;     ...
;             for (int m = 0; m < 4; ++m) { const int row = r0 + ai * HALF + m * 16; const float rq = rsc[row];
;                 const i32x4 i00 = __builtin_bit_cast(i32x4, acc[ai][0][m][0]), i01 = __builtin_bit_cast(i32x4, acc[ai][0][m][1]), i10 = __builtin_bit_cast(i32x4, acc[ai][1][m][0]), i11 = __builtin_bit_cast(i32x4, acc[ai][1][m][1]);
;                 f32x4 a0, a1, b0, b1;
; #pragma unroll
;                 for (int j = 0; j < 4; ++j) { a0[j] = (float)i00[j] * (rq * c00[j]); a1[j] = (float)i01[j] * (rq * c01[j]); b0[j] = (float)i10[j] * (rq * c10[j]); b1[j] = (float)i11[j] * (rq * c11[j]); }
;                 if (kind == 0 || kind == 3) {
;                     if (kind == 0) {
; #pragma unroll
;                         for (int j = 0; j < 4; ++j) { a0[j] = silu_f(a0[j]); a1[j] = silu_f(a1[j]); b0[j] = silu_f(b0[j]); b1[j] = silu_f(b1[j]); } }
;                     u32x4 w; w.x = pk_bf16(a0[0], a0[1]); w.y = pk_bf16(a0[2], a0[3]); w.z = pk_bf16(a1[0], a1[1]); w.w = pk_bf16(a1[2], a1[3]);
;                     *(u32x4*)(O + (size_t)row * 1024 + c0) = w;
;                     w.x = pk_bf16(b0[0], b0[1]); w.y = pk_bf16(b0[2], b0[3]); w.z = pk_bf16(b1[0], b1[1]); w.w = pk_bf16(b1[2], b1[3]);
;                     *(u32x4*)(O + (size_t)row * 1024 + c0 + HALF) = w;
;                 } else { f32x4 v0, v1;
;                     if (kind == 1) { v0 = a0 * b0; v1 = a1 * b1; }
;                     else {
; #pragma unroll
;                         for (int j = 0; j < 4; ++j) { v0[j] = a0[j] * silu_f(b0[j]); v1[j] = a1[j] * silu_f(b1[j]); } }
.LBB0_595:
	s_nop 1
	v_mov_b32_e32 v66, v253
	v_cvt_f32_i32_e32 v63, v63
	v_cvt_f32_i32_e32 v62, v62
	v_cvt_f32_i32_e32 v59, v59
	v_cvt_f32_i32_e32 v58, v58
	v_cvt_f32_i32_e32 v65, v65
	v_cvt_f32_i32_e32 v64, v64
	v_cvt_f32_i32_e32 v61, v61
	v_cvt_f32_i32_e32 v60, v60
	s_cmp_lt_i32 s72, 2
	s_nop 0
	v_pk_mul_f32 v[68:69], v[46:47], v[66:67] op_sel_hi:[1,0]
	v_pk_mul_f32 v[70:71], v[42:43], v[66:67] op_sel_hi:[1,0]
	v_pk_mul_f32 v[72:73], v[48:49], v[66:67] op_sel_hi:[1,0]
	v_pk_mul_f32 v[74:75], v[44:45], v[66:67] op_sel_hi:[1,0]
	v_pk_mul_f32 v[62:63], v[68:69], v[62:63]
	v_pk_mul_f32 v[58:59], v[70:71], v[58:59]
	v_pk_mul_f32 v[64:65], v[72:73], v[64:65]
	v_pk_mul_f32 v[60:61], v[74:75], v[60:61]
	s_cbranch_scc1 .LBB0_598
	s_mov_b64 s[40:41], -1
	s_mov_b64 s[44:45], 0
	s_cmp_lt_i32 s72, 3
	s_mov_b64 s[34:35], 0
	s_cbranch_scc0 .LBB0_599
	v_med3_f32 v67, v62, s63, v196
	v_mul_f32_e32 v67, 0xbfb8aa3b, v67
	v_med3_f32 v68, v58, s63, v196
	v_exp_f32_e32 v67, v67
	v_mul_f32_e32 v68, 0xbfb8aa3b, v68
	v_exp_f32_e32 v69, v68
	v_add_f32_e32 v67, 1.0, v67
	v_rcp_f32_e32 v68, v67
	v_add_f32_e32 v67, 1.0, v69
	v_med3_f32 v69, v63, s63, v196
	v_mul_f32_e32 v69, 0xbfb8aa3b, v69
	v_med3_f32 v70, v59, s63, v196
	v_exp_f32_e32 v69, v69
	v_mul_f32_e32 v70, 0xbfb8aa3b, v70
	v_exp_f32_e32 v70, v70
	v_rcp_f32_e32 v72, v67
	v_add_f32_e32 v67, 1.0, v69
	v_rcp_f32_e32 v69, v67
	v_add_f32_e32 v67, 1.0, v70
	v_med3_f32 v70, v64, s63, v196
	v_mul_f32_e32 v70, 0xbfb8aa3b, v70
	v_med3_f32 v71, v60, s63, v196
	v_exp_f32_e32 v70, v70
	v_mul_f32_e32 v71, 0xbfb8aa3b, v71
	v_exp_f32_e32 v71, v71
	v_rcp_f32_e32 v73, v67
	v_add_f32_e32 v67, 1.0, v70
	v_rcp_f32_e32 v70, v67
	v_add_f32_e32 v67, 1.0, v71
	v_med3_f32 v71, v65, s63, v196
	v_mul_f32_e32 v71, 0xbfb8aa3b, v71
	v_med3_f32 v74, v61, s63, v196
	v_exp_f32_e32 v71, v71
	v_mul_f32_e32 v74, 0xbfb8aa3b, v74
	v_exp_f32_e32 v74, v74
	v_rcp_f32_e32 v76, v67
	v_add_f32_e32 v67, 1.0, v71
	v_rcp_f32_e32 v71, v67
	v_add_f32_e32 v67, 1.0, v74
	v_rcp_f32_e32 v77, v67
	v_pk_mul_f32 v[74:75], v[62:63], v[68:69]
	v_pk_mul_f32 v[70:71], v[64:65], v[70:71]
	v_pk_mul_f32 v[72:73], v[58:59], v[72:73]
	v_pk_mul_f32 v[68:69], v[60:61], v[76:77]
	s_mov_b64 s[40:41], 0
	s_mov_b64 s[34:35], -1
	s_branch .LBB0_599

; __device__ __forceinline__ unsigned pk_bf16(float lo, float hi) { const f32x2_t v = {lo, hi}; return __builtin_bit_cast(unsigned, __builtin_convertvector(v, bf16x2_t)); }
; __device__ __forceinline__ float silu_f(float x) { return x * sigmoid_f(x); }
;     __device__ __forceinline__ bool operator()(f32x4 (&acc)[2][2][4][2], const Unit& u, int wr, int wc, int fr, int fq) const {
;     ...
;                 for (int j = 0; j < 4; ++j) { a0[j] = (float)i00[j] * (rq * c00[j]); a1[j] = (float)i01[j] * (rq * c01[j]); b0[j] = (float)i10[j] * (rq * c10[j]); b1[j] = (float)i11[j] * (rq * c11[j]); }
;                 if (kind == 0 || kind == 3) {
;                     if (kind == 0) {
; #pragma unroll
;                         for (int j = 0; j < 4; ++j) { a0[j] = silu_f(a0[j]); a1[j] = silu_f(a1[j]); b0[j] = silu_f(b0[j]); b1[j] = silu_f(b1[j]); } }
;                     u32x4 w; w.x = pk_bf16(a0[0], a0[1]); w.y = pk_bf16(a0[2], a0[3]); w.z = pk_bf16(a1[0], a1[1]); w.w = pk_bf16(a1[2], a1[3]);
;                     *(u32x4*)(O + (size_t)row * 1024 + c0) = w;
;                     w.x = pk_bf16(b0[0], b0[1]); w.y = pk_bf16(b0[2], b0[3]); w.z = pk_bf16(b1[0], b1[1]); w.w = pk_bf16(b1[2], b1[3]);
;                     *(u32x4*)(O + (size_t)row * 1024 + c0 + HALF) = w;
.LBB0_599:
	v_cvt_f32_i32_e32 v55, v55
	v_cvt_f32_i32_e32 v54, v54
	v_cvt_f32_i32_e32 v77, v51
	v_cvt_f32_i32_e32 v76, v50
	v_pk_mul_f32 v[50:51], v[38:39], v[66:67] op_sel_hi:[1,0]
	v_cvt_f32_i32_e32 v57, v57
	v_pk_mul_f32 v[50:51], v[50:51], v[54:55]
	v_pk_mul_f32 v[54:55], v[34:35], v[66:67] op_sel_hi:[1,0]
	v_cvt_f32_i32_e32 v56, v56
	v_pk_mul_f32 v[54:55], v[54:55], v[76:77]
	v_cvt_f32_i32_e32 v77, v53
	v_cvt_f32_i32_e32 v76, v52
	v_pk_mul_f32 v[52:53], v[40:41], v[66:67] op_sel_hi:[1,0]
	s_and_b64 vcc, exec, s[44:45]
	v_pk_mul_f32 v[52:53], v[52:53], v[56:57]
	v_pk_mul_f32 v[56:57], v[36:37], v[66:67] op_sel_hi:[1,0]
	s_nop 0
	v_pk_mul_f32 v[56:57], v[56:57], v[76:77]
	s_cbranch_vccz .LBB0_603
	s_cmp_lg_u32 s72, 1
	s_mov_b64 s[34:35], -1
	s_cbranch_scc0 .LBB0_602
	v_med3_f32 v75, v56, s63, v196
	v_med3_f32 v68, v62, s63, v196
	v_mul_f32_e32 v75, 0xbfb8aa3b, v75
	v_med3_f32 v67, v54, s63, v196
	v_mul_f32_e32 v68, 0xbfb8aa3b, v68
	v_exp_f32_e32 v75, v75
	v_mul_f32_e32 v67, 0xbfb8aa3b, v67
	v_exp_f32_e32 v69, v68
	v_exp_f32_e32 v67, v67
	v_med3_f32 v68, v58, s63, v196
	v_mul_f32_e32 v68, 0xbfb8aa3b, v68
	v_exp_f32_e32 v71, v68
	v_add_f32_e32 v75, 1.0, v75
	v_rcp_f32_e32 v80, v75
	v_add_f32_e32 v67, 1.0, v67
	v_med3_f32 v75, v64, s63, v196
	v_rcp_f32_e32 v68, v67
	v_add_f32_e32 v67, 1.0, v69
	v_mul_f32_e32 v75, 0xbfb8aa3b, v75
	v_med3_f32 v77, v53, s63, v196
	v_rcp_f32_e32 v70, v67
	v_add_f32_e32 v67, 1.0, v71
	v_exp_f32_e32 v75, v75
	v_mul_f32_e32 v77, 0xbfb8aa3b, v77
	v_med3_f32 v66, v50, s63, v196
	v_med3_f32 v69, v51, s63, v196
	v_med3_f32 v71, v55, s63, v196
	v_med3_f32 v74, v52, s63, v196
	v_exp_f32_e32 v77, v77
	v_mul_f32_e32 v66, 0xbfb8aa3b, v66
	v_mul_f32_e32 v69, 0xbfb8aa3b, v69
	v_mul_f32_e32 v71, 0xbfb8aa3b, v71
	v_mul_f32_e32 v74, 0xbfb8aa3b, v74
	v_exp_f32_e32 v66, v66
	v_exp_f32_e32 v69, v69
	v_exp_f32_e32 v71, v71
	v_exp_f32_e32 v74, v74
	v_add_f32_e32 v75, 1.0, v75
	v_med3_f32 v76, v60, s63, v196
	v_rcp_f32_e32 v84, v75
	v_add_f32_e32 v75, 1.0, v77
	v_mul_f32_e32 v76, 0xbfb8aa3b, v76
	v_med3_f32 v77, v57, s63, v196
	v_add_f32_e32 v66, 1.0, v66
	v_rcp_f32_e32 v72, v67
	v_add_f32_e32 v67, 1.0, v69
	v_add_f32_e32 v69, 1.0, v71
	v_add_f32_e32 v74, 1.0, v74
	v_exp_f32_e32 v76, v76
	v_mul_f32_e32 v77, 0xbfb8aa3b, v77
	v_rcp_f32_e32 v66, v66
	v_rcp_f32_e32 v67, v67
	v_rcp_f32_e32 v69, v69
	v_rcp_f32_e32 v74, v74
	v_rcp_f32_e32 v75, v75
	v_exp_f32_e32 v77, v77
	v_add_f32_e32 v76, 1.0, v76
	v_rcp_f32_e32 v88, v76
	v_pk_mul_f32 v[78:79], v[50:51], v[66:67]
	v_pk_mul_f32 v[66:67], v[52:53], v[74:75]
	v_add_f32_e32 v74, 1.0, v77
	v_pk_mul_f32 v[76:77], v[54:55], v[68:69]
	v_med3_f32 v68, v65, s63, v196
	v_med3_f32 v71, v63, s63, v196
	v_med3_f32 v73, v59, s63, v196
	v_mul_f32_e32 v68, 0xbfb8aa3b, v68
	v_med3_f32 v69, v61, s63, v196
	v_mul_f32_e32 v71, 0xbfb8aa3b, v71
	v_mul_f32_e32 v73, 0xbfb8aa3b, v73
	v_exp_f32_e32 v68, v68
	v_mul_f32_e32 v69, 0xbfb8aa3b, v69
	v_exp_f32_e32 v71, v71
	v_exp_f32_e32 v73, v73
	v_exp_f32_e32 v69, v69
	v_add_f32_e32 v68, 1.0, v68
	v_add_f32_e32 v71, 1.0, v71
	v_add_f32_e32 v73, 1.0, v73
	v_rcp_f32_e32 v85, v68
	v_add_f32_e32 v68, 1.0, v69
	v_rcp_f32_e32 v71, v71
	v_rcp_f32_e32 v73, v73
	v_rcp_f32_e32 v81, v74
	v_rcp_f32_e32 v89, v68
	v_pk_mul_f32 v[82:83], v[62:63], v[70:71]
	v_pk_mul_f32 v[84:85], v[64:65], v[84:85]
	v_pk_mul_f32 v[80:81], v[56:57], v[80:81]
	v_pk_mul_f32 v[86:87], v[58:59], v[72:73]
	v_pk_mul_f32 v[88:89], v[60:61], v[88:89]
	s_mov_b64 s[40:41], -1
	s_mov_b64 s[34:35], 0

; __device__ __forceinline__ unsigned pk_bf16(float lo, float hi) { const f32x2_t v = {lo, hi}; return __builtin_bit_cast(unsigned, __builtin_convertvector(v, bf16x2_t)); }
; __device__ __forceinline__ float silu_f(float x) { return x * sigmoid_f(x); }
;     __device__ __forceinline__ bool operator()(f32x4 (&acc)[2][2][4][2], const Unit& u, int wr, int wc, int fr, int fq) const {
;     ...
;             for (int m = 0; m < 4; ++m) { const int row = r0 + ai * HALF + m * 16; const float rq = rsc[row];
;                 const i32x4 i00 = __builtin_bit_cast(i32x4, acc[ai][0][m][0]), i01 = __builtin_bit_cast(i32x4, acc[ai][0][m][1]), i10 = __builtin_bit_cast(i32x4, acc[ai][1][m][0]), i11 = __builtin_bit_cast(i32x4, acc[ai][1][m][1]);
;                 f32x4 a0, a1, b0, b1;
; #pragma unroll
;                 for (int j = 0; j < 4; ++j) { a0[j] = (float)i00[j] * (rq * c00[j]); a1[j] = (float)i01[j] * (rq * c01[j]); b0[j] = (float)i10[j] * (rq * c10[j]); b1[j] = (float)i11[j] * (rq * c11[j]); }
;                 if (kind == 0 || kind == 3) {
;                     if (kind == 0) {
; #pragma unroll
;                         for (int j = 0; j < 4; ++j) { a0[j] = silu_f(a0[j]); a1[j] = silu_f(a1[j]); b0[j] = silu_f(b0[j]); b1[j] = silu_f(b1[j]); } }
;                     u32x4 w; w.x = pk_bf16(a0[0], a0[1]); w.y = pk_bf16(a0[2], a0[3]); w.z = pk_bf16(a1[0], a1[1]); w.w = pk_bf16(a1[2], a1[3]);
;                     *(u32x4*)(O + (size_t)row * 1024 + c0) = w;
;                     w.x = pk_bf16(b0[0], b0[1]); w.y = pk_bf16(b0[2], b0[3]); w.z = pk_bf16(b1[0], b1[1]); w.w = pk_bf16(b1[2], b1[3]);
;                     *(u32x4*)(O + (size_t)row * 1024 + c0 + HALF) = w;
;                 } else { f32x4 v0, v1;
;                     if (kind == 1) { v0 = a0 * b0; v1 = a1 * b1; }
;                     else {
; #pragma unroll
;                         for (int j = 0; j < 4; ++j) { v0[j] = a0[j] * silu_f(b0[j]); v1[j] = a1[j] * silu_f(b1[j]); } }
.LBB0_608:
	s_nop 1
	v_mov_b32_e32 v50, v254
	v_cvt_f32_i32_e32 v31, v31
	v_cvt_f32_i32_e32 v30, v30
	v_cvt_f32_i32_e32 v27, v27
	v_cvt_f32_i32_e32 v26, v26
	v_cvt_f32_i32_e32 v33, v33
	v_cvt_f32_i32_e32 v32, v32
	v_cvt_f32_i32_e32 v29, v29
	v_cvt_f32_i32_e32 v28, v28
	s_cmp_lt_i32 s72, 2
	s_nop 0
	v_pk_mul_f32 v[52:53], v[46:47], v[50:51] op_sel_hi:[1,0]
	v_pk_mul_f32 v[54:55], v[42:43], v[50:51] op_sel_hi:[1,0]
	v_pk_mul_f32 v[56:57], v[48:49], v[50:51] op_sel_hi:[1,0]
	v_pk_mul_f32 v[58:59], v[44:45], v[50:51] op_sel_hi:[1,0]
	v_pk_mul_f32 v[30:31], v[52:53], v[30:31]
	v_pk_mul_f32 v[26:27], v[54:55], v[26:27]
	v_pk_mul_f32 v[32:33], v[56:57], v[32:33]
	v_pk_mul_f32 v[28:29], v[58:59], v[28:29]
	s_cbranch_scc1 .LBB0_611
	s_mov_b64 s[40:41], -1
	s_mov_b64 s[44:45], 0
	s_cmp_lt_i32 s72, 3
	s_mov_b64 s[34:35], 0
	s_cbranch_scc0 .LBB0_612
	v_med3_f32 v51, v30, s63, v196
	v_mul_f32_e32 v51, 0xbfb8aa3b, v51
	v_med3_f32 v52, v26, s63, v196
	v_exp_f32_e32 v51, v51
	v_mul_f32_e32 v52, 0xbfb8aa3b, v52
	v_exp_f32_e32 v53, v52
	v_add_f32_e32 v51, 1.0, v51
	v_rcp_f32_e32 v52, v51
	v_add_f32_e32 v51, 1.0, v53
	v_med3_f32 v53, v31, s63, v196
	v_mul_f32_e32 v53, 0xbfb8aa3b, v53
	v_med3_f32 v54, v27, s63, v196
	v_exp_f32_e32 v53, v53
	v_mul_f32_e32 v54, 0xbfb8aa3b, v54
	v_exp_f32_e32 v54, v54
	v_rcp_f32_e32 v56, v51
	v_add_f32_e32 v51, 1.0, v53
	v_rcp_f32_e32 v53, v51
	v_add_f32_e32 v51, 1.0, v54
	v_med3_f32 v54, v32, s63, v196
	v_mul_f32_e32 v54, 0xbfb8aa3b, v54
	v_med3_f32 v55, v28, s63, v196
	v_exp_f32_e32 v54, v54
	v_mul_f32_e32 v55, 0xbfb8aa3b, v55
	v_exp_f32_e32 v55, v55
	v_rcp_f32_e32 v57, v51
	v_add_f32_e32 v51, 1.0, v54
	v_rcp_f32_e32 v54, v51
	v_add_f32_e32 v51, 1.0, v55
	v_med3_f32 v55, v33, s63, v196
	v_mul_f32_e32 v55, 0xbfb8aa3b, v55
	v_med3_f32 v58, v29, s63, v196
	v_exp_f32_e32 v55, v55
	v_mul_f32_e32 v58, 0xbfb8aa3b, v58
	v_exp_f32_e32 v58, v58
	v_rcp_f32_e32 v60, v51
	v_add_f32_e32 v51, 1.0, v55
	v_rcp_f32_e32 v55, v51
	v_add_f32_e32 v51, 1.0, v58
	v_rcp_f32_e32 v61, v51
	v_pk_mul_f32 v[58:59], v[30:31], v[52:53]
	v_pk_mul_f32 v[54:55], v[32:33], v[54:55]
	v_pk_mul_f32 v[56:57], v[26:27], v[56:57]
	v_pk_mul_f32 v[52:53], v[28:29], v[60:61]
	s_mov_b64 s[40:41], 0
	s_mov_b64 s[34:35], -1
	s_branch .LBB0_612

; __device__ __forceinline__ unsigned pk_bf16(float lo, float hi) { const f32x2_t v = {lo, hi}; return __builtin_bit_cast(unsigned, __builtin_convertvector(v, bf16x2_t)); }
; __device__ __forceinline__ float silu_f(float x) { return x * sigmoid_f(x); }
;     __device__ __forceinline__ bool operator()(f32x4 (&acc)[2][2][4][2], const Unit& u, int wr, int wc, int fr, int fq) const {
;     ...
;                 for (int j = 0; j < 4; ++j) { a0[j] = (float)i00[j] * (rq * c00[j]); a1[j] = (float)i01[j] * (rq * c01[j]); b0[j] = (float)i10[j] * (rq * c10[j]); b1[j] = (float)i11[j] * (rq * c11[j]); }
;                 if (kind == 0 || kind == 3) {
;                     if (kind == 0) {
; #pragma unroll
;                         for (int j = 0; j < 4; ++j) { a0[j] = silu_f(a0[j]); a1[j] = silu_f(a1[j]); b0[j] = silu_f(b0[j]); b1[j] = silu_f(b1[j]); } }
;                     u32x4 w; w.x = pk_bf16(a0[0], a0[1]); w.y = pk_bf16(a0[2], a0[3]); w.z = pk_bf16(a1[0], a1[1]); w.w = pk_bf16(a1[2], a1[3]);
;                     *(u32x4*)(O + (size_t)row * 1024 + c0) = w;
;                     w.x = pk_bf16(b0[0], b0[1]); w.y = pk_bf16(b0[2], b0[3]); w.z = pk_bf16(b1[0], b1[1]); w.w = pk_bf16(b1[2], b1[3]);
;                     *(u32x4*)(O + (size_t)row * 1024 + c0 + HALF) = w;
.LBB0_612:
	v_cvt_f32_i32_e32 v23, v23
	v_cvt_f32_i32_e32 v22, v22
	v_cvt_f32_i32_e32 v61, v19
	v_cvt_f32_i32_e32 v60, v18
	v_pk_mul_f32 v[18:19], v[38:39], v[50:51] op_sel_hi:[1,0]
	v_cvt_f32_i32_e32 v25, v25
	v_pk_mul_f32 v[18:19], v[18:19], v[22:23]
	v_pk_mul_f32 v[22:23], v[34:35], v[50:51] op_sel_hi:[1,0]
	v_cvt_f32_i32_e32 v24, v24
	v_pk_mul_f32 v[22:23], v[22:23], v[60:61]
	v_cvt_f32_i32_e32 v61, v21
	v_cvt_f32_i32_e32 v60, v20
	v_pk_mul_f32 v[20:21], v[40:41], v[50:51] op_sel_hi:[1,0]
	s_and_b64 vcc, exec, s[44:45]
	v_pk_mul_f32 v[20:21], v[20:21], v[24:25]
	v_pk_mul_f32 v[24:25], v[36:37], v[50:51] op_sel_hi:[1,0]
	s_nop 0
	v_pk_mul_f32 v[24:25], v[24:25], v[60:61]
	s_cbranch_vccz .LBB0_616
	s_cmp_lg_u32 s72, 1
	s_mov_b64 s[34:35], -1
	s_cbranch_scc0 .LBB0_615
	v_med3_f32 v59, v24, s63, v196
	v_med3_f32 v52, v30, s63, v196
	v_mul_f32_e32 v59, 0xbfb8aa3b, v59
	v_med3_f32 v51, v22, s63, v196
	v_mul_f32_e32 v52, 0xbfb8aa3b, v52
	v_exp_f32_e32 v59, v59
	v_mul_f32_e32 v51, 0xbfb8aa3b, v51
	v_exp_f32_e32 v53, v52
	v_exp_f32_e32 v51, v51
	v_med3_f32 v52, v26, s63, v196
	v_mul_f32_e32 v52, 0xbfb8aa3b, v52
	v_exp_f32_e32 v55, v52
	v_add_f32_e32 v59, 1.0, v59
	v_rcp_f32_e32 v64, v59
	v_add_f32_e32 v51, 1.0, v51
	v_med3_f32 v59, v32, s63, v196
	v_rcp_f32_e32 v52, v51
	v_add_f32_e32 v51, 1.0, v53
	v_mul_f32_e32 v59, 0xbfb8aa3b, v59
	v_med3_f32 v61, v21, s63, v196
	v_rcp_f32_e32 v54, v51
	v_add_f32_e32 v51, 1.0, v55
	v_exp_f32_e32 v59, v59
	v_mul_f32_e32 v61, 0xbfb8aa3b, v61
	v_med3_f32 v50, v18, s63, v196
	v_med3_f32 v53, v19, s63, v196
	v_med3_f32 v55, v23, s63, v196
	v_med3_f32 v58, v20, s63, v196
	v_exp_f32_e32 v61, v61
	v_mul_f32_e32 v50, 0xbfb8aa3b, v50
	v_mul_f32_e32 v53, 0xbfb8aa3b, v53
	v_mul_f32_e32 v55, 0xbfb8aa3b, v55
	v_mul_f32_e32 v58, 0xbfb8aa3b, v58
	v_exp_f32_e32 v50, v50
	v_exp_f32_e32 v53, v53
	v_exp_f32_e32 v55, v55
	v_exp_f32_e32 v58, v58
	v_add_f32_e32 v59, 1.0, v59
	v_med3_f32 v60, v28, s63, v196
	v_rcp_f32_e32 v68, v59
	v_add_f32_e32 v59, 1.0, v61
	v_mul_f32_e32 v60, 0xbfb8aa3b, v60
	v_med3_f32 v61, v25, s63, v196
	v_add_f32_e32 v50, 1.0, v50
	v_rcp_f32_e32 v56, v51
	v_add_f32_e32 v51, 1.0, v53
	v_add_f32_e32 v53, 1.0, v55
	v_add_f32_e32 v58, 1.0, v58
	v_exp_f32_e32 v60, v60
	v_mul_f32_e32 v61, 0xbfb8aa3b, v61
	v_rcp_f32_e32 v50, v50
	v_rcp_f32_e32 v51, v51
	v_rcp_f32_e32 v53, v53
	v_rcp_f32_e32 v58, v58
	v_rcp_f32_e32 v59, v59
	v_exp_f32_e32 v61, v61
	v_add_f32_e32 v60, 1.0, v60
	v_rcp_f32_e32 v72, v60
	v_pk_mul_f32 v[62:63], v[18:19], v[50:51]
	v_pk_mul_f32 v[50:51], v[20:21], v[58:59]
	v_add_f32_e32 v58, 1.0, v61
	v_pk_mul_f32 v[60:61], v[22:23], v[52:53]
	v_med3_f32 v52, v33, s63, v196
	v_med3_f32 v55, v31, s63, v196
	v_med3_f32 v57, v27, s63, v196
	v_mul_f32_e32 v52, 0xbfb8aa3b, v52
	v_med3_f32 v53, v29, s63, v196
	v_mul_f32_e32 v55, 0xbfb8aa3b, v55
	v_mul_f32_e32 v57, 0xbfb8aa3b, v57
	v_exp_f32_e32 v52, v52
	v_mul_f32_e32 v53, 0xbfb8aa3b, v53
	v_exp_f32_e32 v55, v55
	v_exp_f32_e32 v57, v57
	v_exp_f32_e32 v53, v53
	v_add_f32_e32 v52, 1.0, v52
	v_add_f32_e32 v55, 1.0, v55
	v_add_f32_e32 v57, 1.0, v57
	v_rcp_f32_e32 v69, v52
	v_add_f32_e32 v52, 1.0, v53
	v_rcp_f32_e32 v55, v55
	v_rcp_f32_e32 v57, v57
	v_rcp_f32_e32 v65, v58
	v_rcp_f32_e32 v73, v52
	v_pk_mul_f32 v[66:67], v[30:31], v[54:55]
	v_pk_mul_f32 v[68:69], v[32:33], v[68:69]
	v_pk_mul_f32 v[64:65], v[24:25], v[64:65]
	v_pk_mul_f32 v[70:71], v[26:27], v[56:57]
	v_pk_mul_f32 v[72:73], v[28:29], v[72:73]
	s_mov_b64 s[40:41], -1
	s_mov_b64 s[34:35], 0

; __device__ __forceinline__ unsigned pk_bf16(float lo, float hi) { const f32x2_t v = {lo, hi}; return __builtin_bit_cast(unsigned, __builtin_convertvector(v, bf16x2_t)); }
; __device__ __forceinline__ float silu_f(float x) { return x * sigmoid_f(x); }
;     __device__ __forceinline__ bool operator()(f32x4 (&acc)[2][2][4][2], const Unit& u, int wr, int wc, int fr, int fq) const {
;     ...
;             for (int m = 0; m < 4; ++m) { const int row = r0 + ai * HALF + m * 16; const float rq = rsc[row];
;                 const i32x4 i00 = __builtin_bit_cast(i32x4, acc[ai][0][m][0]), i01 = __builtin_bit_cast(i32x4, acc[ai][0][m][1]), i10 = __builtin_bit_cast(i32x4, acc[ai][1][m][0]), i11 = __builtin_bit_cast(i32x4, acc[ai][1][m][1]);
;                 f32x4 a0, a1, b0, b1;
; #pragma unroll
;                 for (int j = 0; j < 4; ++j) { a0[j] = (float)i00[j] * (rq * c00[j]); a1[j] = (float)i01[j] * (rq * c01[j]); b0[j] = (float)i10[j] * (rq * c10[j]); b1[j] = (float)i11[j] * (rq * c11[j]); }
;                 if (kind == 0 || kind == 3) {
;                     if (kind == 0) {
; #pragma unroll
;                         for (int j = 0; j < 4; ++j) { a0[j] = silu_f(a0[j]); a1[j] = silu_f(a1[j]); b0[j] = silu_f(b0[j]); b1[j] = silu_f(b1[j]); } }
;                     u32x4 w; w.x = pk_bf16(a0[0], a0[1]); w.y = pk_bf16(a0[2], a0[3]); w.z = pk_bf16(a1[0], a1[1]); w.w = pk_bf16(a1[2], a1[3]);
;                     *(u32x4*)(O + (size_t)row * 1024 + c0) = w;
;                     w.x = pk_bf16(b0[0], b0[1]); w.y = pk_bf16(b0[2], b0[3]); w.z = pk_bf16(b1[0], b1[1]); w.w = pk_bf16(b1[2], b1[3]);
;                     *(u32x4*)(O + (size_t)row * 1024 + c0 + HALF) = w;
;                 } else { f32x4 v0, v1;
;                     if (kind == 1) { v0 = a0 * b0; v1 = a1 * b1; }
;                     else {
; #pragma unroll
;                         for (int j = 0; j < 4; ++j) { v0[j] = a0[j] * silu_f(b0[j]); v1[j] = a1[j] * silu_f(b1[j]); } }
.LBB0_621:
	s_nop 1
	v_mov_b32_e32 v18, v255
	v_cvt_f32_i32_e32 v15, v15
	v_cvt_f32_i32_e32 v14, v14
	v_cvt_f32_i32_e32 v11, v11
	v_cvt_f32_i32_e32 v10, v10
	v_cvt_f32_i32_e32 v17, v17
	v_cvt_f32_i32_e32 v16, v16
	v_cvt_f32_i32_e32 v13, v13
	v_cvt_f32_i32_e32 v12, v12
	s_cmp_lt_i32 s72, 2
	s_nop 0
	v_pk_mul_f32 v[20:21], v[46:47], v[18:19] op_sel_hi:[1,0]
	v_pk_mul_f32 v[22:23], v[42:43], v[18:19] op_sel_hi:[1,0]
	v_pk_mul_f32 v[24:25], v[48:49], v[18:19] op_sel_hi:[1,0]
	v_pk_mul_f32 v[26:27], v[44:45], v[18:19] op_sel_hi:[1,0]
	v_pk_mul_f32 v[14:15], v[20:21], v[14:15]
	v_pk_mul_f32 v[10:11], v[22:23], v[10:11]
	v_pk_mul_f32 v[16:17], v[24:25], v[16:17]
	v_pk_mul_f32 v[12:13], v[26:27], v[12:13]
	s_cbranch_scc1 .LBB0_624
	s_mov_b64 s[40:41], -1
	s_mov_b64 s[44:45], 0
	s_cmp_lt_i32 s72, 3
	s_mov_b64 s[34:35], 0
	s_cbranch_scc0 .LBB0_625
	v_med3_f32 v19, v14, s63, v196
	v_mul_f32_e32 v19, 0xbfb8aa3b, v19
	v_med3_f32 v20, v10, s63, v196
	v_exp_f32_e32 v19, v19
	v_mul_f32_e32 v20, 0xbfb8aa3b, v20
	v_exp_f32_e32 v21, v20
	v_add_f32_e32 v19, 1.0, v19
	v_rcp_f32_e32 v20, v19
	v_add_f32_e32 v19, 1.0, v21
	v_med3_f32 v21, v15, s63, v196
	v_mul_f32_e32 v21, 0xbfb8aa3b, v21
	v_med3_f32 v22, v11, s63, v196
	v_exp_f32_e32 v21, v21
	v_mul_f32_e32 v22, 0xbfb8aa3b, v22
	v_exp_f32_e32 v22, v22
	v_rcp_f32_e32 v24, v19
	v_add_f32_e32 v19, 1.0, v21
	v_rcp_f32_e32 v21, v19
	v_add_f32_e32 v19, 1.0, v22
	v_med3_f32 v22, v16, s63, v196
	v_mul_f32_e32 v22, 0xbfb8aa3b, v22
	v_med3_f32 v23, v12, s63, v196
	v_exp_f32_e32 v22, v22
	v_mul_f32_e32 v23, 0xbfb8aa3b, v23
	v_exp_f32_e32 v23, v23
	v_rcp_f32_e32 v25, v19
	v_add_f32_e32 v19, 1.0, v22
	v_rcp_f32_e32 v22, v19
	v_add_f32_e32 v19, 1.0, v23
	v_med3_f32 v23, v17, s63, v196
	v_mul_f32_e32 v23, 0xbfb8aa3b, v23
	v_med3_f32 v26, v13, s63, v196
	v_exp_f32_e32 v23, v23
	v_mul_f32_e32 v26, 0xbfb8aa3b, v26
	v_exp_f32_e32 v26, v26
	v_rcp_f32_e32 v28, v19
	v_add_f32_e32 v19, 1.0, v23
	v_rcp_f32_e32 v23, v19
	v_add_f32_e32 v19, 1.0, v26
	v_rcp_f32_e32 v29, v19
	v_pk_mul_f32 v[26:27], v[14:15], v[20:21]
	v_pk_mul_f32 v[22:23], v[16:17], v[22:23]
	v_pk_mul_f32 v[24:25], v[10:11], v[24:25]
	v_pk_mul_f32 v[20:21], v[12:13], v[28:29]
	s_mov_b64 s[40:41], 0
	s_mov_b64 s[34:35], -1
	s_branch .LBB0_625

; __device__ __forceinline__ unsigned pk_bf16(float lo, float hi) { const f32x2_t v = {lo, hi}; return __builtin_bit_cast(unsigned, __builtin_convertvector(v, bf16x2_t)); }
; __device__ __forceinline__ float silu_f(float x) { return x * sigmoid_f(x); }
;     __device__ __forceinline__ bool operator()(f32x4 (&acc)[2][2][4][2], const Unit& u, int wr, int wc, int fr, int fq) const {
;     ...
;                 for (int j = 0; j < 4; ++j) { a0[j] = (float)i00[j] * (rq * c00[j]); a1[j] = (float)i01[j] * (rq * c01[j]); b0[j] = (float)i10[j] * (rq * c10[j]); b1[j] = (float)i11[j] * (rq * c11[j]); }
;                 if (kind == 0 || kind == 3) {
;                     if (kind == 0) {
; #pragma unroll
;                         for (int j = 0; j < 4; ++j) { a0[j] = silu_f(a0[j]); a1[j] = silu_f(a1[j]); b0[j] = silu_f(b0[j]); b1[j] = silu_f(b1[j]); } }
;                     u32x4 w; w.x = pk_bf16(a0[0], a0[1]); w.y = pk_bf16(a0[2], a0[3]); w.z = pk_bf16(a1[0], a1[1]); w.w = pk_bf16(a1[2], a1[3]);
;                     *(u32x4*)(O + (size_t)row * 1024 + c0) = w;
;                     w.x = pk_bf16(b0[0], b0[1]); w.y = pk_bf16(b0[2], b0[3]); w.z = pk_bf16(b1[0], b1[1]); w.w = pk_bf16(b1[2], b1[3]);
;                     *(u32x4*)(O + (size_t)row * 1024 + c0 + HALF) = w;
.LBB0_625:
	v_cvt_f32_i32_e32 v7, v7
	v_cvt_f32_i32_e32 v6, v6
	v_cvt_f32_i32_e32 v29, v3
	v_cvt_f32_i32_e32 v28, v2
	v_pk_mul_f32 v[2:3], v[38:39], v[18:19] op_sel_hi:[1,0]
	v_cvt_f32_i32_e32 v9, v9
	v_pk_mul_f32 v[2:3], v[2:3], v[6:7]
	v_pk_mul_f32 v[6:7], v[34:35], v[18:19] op_sel_hi:[1,0]
	v_cvt_f32_i32_e32 v8, v8
	v_pk_mul_f32 v[6:7], v[6:7], v[28:29]
	v_cvt_f32_i32_e32 v29, v5
	v_cvt_f32_i32_e32 v28, v4
	v_pk_mul_f32 v[4:5], v[40:41], v[18:19] op_sel_hi:[1,0]
	s_and_b64 vcc, exec, s[44:45]
	v_pk_mul_f32 v[4:5], v[4:5], v[8:9]
	v_pk_mul_f32 v[8:9], v[36:37], v[18:19] op_sel_hi:[1,0]
	s_nop 0
	v_pk_mul_f32 v[8:9], v[8:9], v[28:29]
	s_cbranch_vccz .LBB0_629
	s_cmp_lg_u32 s72, 1
	s_mov_b64 s[34:35], -1
	s_cbranch_scc0 .LBB0_628
	v_med3_f32 v27, v8, s63, v196
	v_med3_f32 v20, v14, s63, v196
	v_mul_f32_e32 v27, 0xbfb8aa3b, v27
	v_med3_f32 v19, v6, s63, v196
	v_mul_f32_e32 v20, 0xbfb8aa3b, v20
	v_exp_f32_e32 v27, v27
	v_mul_f32_e32 v19, 0xbfb8aa3b, v19
	v_exp_f32_e32 v21, v20
	v_exp_f32_e32 v19, v19
	v_med3_f32 v20, v10, s63, v196
	v_mul_f32_e32 v20, 0xbfb8aa3b, v20
	v_exp_f32_e32 v23, v20
	v_add_f32_e32 v27, 1.0, v27
	v_rcp_f32_e32 v32, v27
	v_add_f32_e32 v19, 1.0, v19
	v_med3_f32 v27, v16, s63, v196
	v_rcp_f32_e32 v20, v19
	v_add_f32_e32 v19, 1.0, v21
	v_mul_f32_e32 v27, 0xbfb8aa3b, v27
	v_med3_f32 v29, v5, s63, v196
	v_rcp_f32_e32 v22, v19
	v_add_f32_e32 v19, 1.0, v23
	v_exp_f32_e32 v27, v27
	v_mul_f32_e32 v29, 0xbfb8aa3b, v29
	v_med3_f32 v18, v2, s63, v196
	v_med3_f32 v21, v3, s63, v196
	v_med3_f32 v23, v7, s63, v196
	v_med3_f32 v26, v4, s63, v196
	v_exp_f32_e32 v29, v29
	v_mul_f32_e32 v18, 0xbfb8aa3b, v18
	v_mul_f32_e32 v21, 0xbfb8aa3b, v21
	v_mul_f32_e32 v23, 0xbfb8aa3b, v23
	v_mul_f32_e32 v26, 0xbfb8aa3b, v26
	v_exp_f32_e32 v18, v18
	v_exp_f32_e32 v21, v21
	v_exp_f32_e32 v23, v23
	v_exp_f32_e32 v26, v26
	v_add_f32_e32 v27, 1.0, v27
	v_med3_f32 v28, v12, s63, v196
	v_rcp_f32_e32 v36, v27
	v_add_f32_e32 v27, 1.0, v29
	v_mul_f32_e32 v28, 0xbfb8aa3b, v28
	v_med3_f32 v29, v9, s63, v196
	v_add_f32_e32 v18, 1.0, v18
	v_rcp_f32_e32 v24, v19
	v_add_f32_e32 v19, 1.0, v21
	v_add_f32_e32 v21, 1.0, v23
	v_add_f32_e32 v26, 1.0, v26
	v_exp_f32_e32 v28, v28
	v_mul_f32_e32 v29, 0xbfb8aa3b, v29
	v_rcp_f32_e32 v18, v18
	v_rcp_f32_e32 v19, v19
	v_rcp_f32_e32 v21, v21
	v_rcp_f32_e32 v26, v26
	v_rcp_f32_e32 v27, v27
	v_exp_f32_e32 v29, v29
	v_add_f32_e32 v28, 1.0, v28
	v_rcp_f32_e32 v40, v28
	v_pk_mul_f32 v[30:31], v[2:3], v[18:19]
	v_pk_mul_f32 v[18:19], v[4:5], v[26:27]
	v_add_f32_e32 v26, 1.0, v29
	v_pk_mul_f32 v[28:29], v[6:7], v[20:21]
	v_med3_f32 v20, v17, s63, v196
	v_med3_f32 v23, v15, s63, v196
	v_med3_f32 v25, v11, s63, v196
	v_mul_f32_e32 v20, 0xbfb8aa3b, v20
	v_med3_f32 v21, v13, s63, v196
	v_mul_f32_e32 v23, 0xbfb8aa3b, v23
	v_mul_f32_e32 v25, 0xbfb8aa3b, v25
	v_exp_f32_e32 v20, v20
	v_mul_f32_e32 v21, 0xbfb8aa3b, v21
	v_exp_f32_e32 v23, v23
	v_exp_f32_e32 v25, v25
	v_exp_f32_e32 v21, v21
	v_add_f32_e32 v20, 1.0, v20
	v_add_f32_e32 v23, 1.0, v23
	v_add_f32_e32 v25, 1.0, v25
	v_rcp_f32_e32 v37, v20
	v_add_f32_e32 v20, 1.0, v21
	v_rcp_f32_e32 v23, v23
	v_rcp_f32_e32 v25, v25
	v_rcp_f32_e32 v33, v26
	v_rcp_f32_e32 v41, v20
	v_pk_mul_f32 v[34:35], v[14:15], v[22:23]
	v_pk_mul_f32 v[36:37], v[16:17], v[36:37]
	v_pk_mul_f32 v[32:33], v[8:9], v[32:33]
	v_pk_mul_f32 v[38:39], v[10:11], v[24:25]
	v_pk_mul_f32 v[40:41], v[12:13], v[40:41]
	s_mov_b64 s[40:41], -1
	s_mov_b64 s[34:35], 0

; template <int MODE  , class Epi, class Sched>
; __device__ __forceinline__ void gemm_phase(LAS unsigned char* lds, const GemmDesc g, const Sched& S, const Epi& E) {
;     ...
; #pragma unroll
;             for (int a = 0; a < 2; ++a)
; #pragma unroll
;                 for (int b = 0; b < 2; ++b)
; #pragma unroll
;                     for (int m = 0; m < 4; ++m)
; #pragma unroll
;                         for (int n = 0; n < 2; ++n) acc[a][b][m][n] = (f32x4){0.f, 0.f, 0.f, 0.f};
.LBB0_736:
	s_add_u32 s77, s46, 0x100
	v_mov_b32_e32 v18, 0
	s_addc_u32 s78, s47, 0
	s_mov_b32 s79, -2
	v_mov_b32_e32 v19, v18
	v_mov_b64_e32 v[20:21], v[18:19]
	v_mov_b64_e32 v[22:23], v[18:19]
	v_mov_b64_e32 v[24:25], v[18:19]
	v_mov_b64_e32 v[34:35], v[18:19]
	v_mov_b64_e32 v[36:37], v[18:19]
	v_mov_b64_e32 v[38:39], v[18:19]
	v_mov_b64_e32 v[40:41], v[18:19]
	v_mov_b64_e32 v[50:51], v[18:19]
	v_mov_b64_e32 v[52:53], v[18:19]
	v_mov_b64_e32 v[54:55], v[18:19]
	v_mov_b64_e32 v[56:57], v[18:19]
	v_mov_b64_e32 v[66:67], v[18:19]
	v_mov_b64_e32 v[68:69], v[18:19]
	v_mov_b64_e32 v[70:71], v[18:19]
	v_mov_b64_e32 v[72:73], v[18:19]
	v_mov_b64_e32 v[26:27], v[18:19]
	v_mov_b64_e32 v[28:29], v[18:19]
	v_mov_b64_e32 v[30:31], v[18:19]
	v_mov_b64_e32 v[32:33], v[18:19]
	v_mov_b64_e32 v[42:43], v[18:19]
	v_mov_b64_e32 v[44:45], v[18:19]
	v_mov_b64_e32 v[46:47], v[18:19]
	v_mov_b64_e32 v[48:49], v[18:19]
	v_mov_b64_e32 v[58:59], v[18:19]
	v_mov_b64_e32 v[60:61], v[18:19]
	v_mov_b64_e32 v[62:63], v[18:19]
	v_mov_b64_e32 v[64:65], v[18:19]
	v_mov_b64_e32 v[74:75], v[18:19]
	v_mov_b64_e32 v[76:77], v[18:19]
	v_mov_b64_e32 v[78:79], v[18:19]
	v_mov_b64_e32 v[80:81], v[18:19]
	v_mov_b64_e32 v[82:83], v[18:19]
	v_mov_b64_e32 v[84:85], v[18:19]
	v_mov_b64_e32 v[86:87], v[18:19]
	v_mov_b64_e32 v[88:89], v[18:19]
	v_mov_b64_e32 v[98:99], v[18:19]
	v_mov_b64_e32 v[100:101], v[18:19]
	v_mov_b64_e32 v[102:103], v[18:19]
	v_mov_b64_e32 v[104:105], v[18:19]
	v_mov_b64_e32 v[114:115], v[18:19]
	v_mov_b64_e32 v[116:117], v[18:19]
	v_mov_b64_e32 v[118:119], v[18:19]
	v_mov_b64_e32 v[120:121], v[18:19]
	v_mov_b64_e32 v[130:131], v[18:19]
	v_mov_b64_e32 v[132:133], v[18:19]
	v_mov_b64_e32 v[134:135], v[18:19]
	v_mov_b64_e32 v[136:137], v[18:19]
	v_mov_b64_e32 v[90:91], v[18:19]
	v_mov_b64_e32 v[92:93], v[18:19]
	v_mov_b64_e32 v[94:95], v[18:19]
	v_mov_b64_e32 v[96:97], v[18:19]
	v_mov_b64_e32 v[106:107], v[18:19]
	v_mov_b64_e32 v[108:109], v[18:19]
	v_mov_b64_e32 v[110:111], v[18:19]
	v_mov_b64_e32 v[112:113], v[18:19]
	v_mov_b64_e32 v[122:123], v[18:19]
	v_mov_b64_e32 v[124:125], v[18:19]
	v_mov_b64_e32 v[126:127], v[18:19]
	v_mov_b64_e32 v[128:129], v[18:19]
	v_mov_b64_e32 v[138:139], v[18:19]
	v_mov_b64_e32 v[140:141], v[18:19]
	v_mov_b64_e32 v[142:143], v[18:19]
	v_mov_b64_e32 v[144:145], v[18:19]

; #define G_STAGE(bufoff, gbase, voff) do { _Pragma("unroll") for (int _i = 0; _i < 2; ++_i) \
;         __builtin_amdgcn_global_load_lds((const unsigned*)((const char*)(gbase) + (voff)[_i]), (LAS unsigned*)(lds + (bufoff) + ldsw + _i * 8192), 16, 0, 0); } while (0)
; #define G_WAIT_V(n) asm volatile("s_waitcnt vmcnt(" #n ")" ::: "memory")
; #define G_BAR __builtin_amdgcn_s_barrier()
; template <int MODE  , class Epi, class Sched>
; __device__ __forceinline__ void gemm_phase(LAS unsigned char* lds, const GemmDesc g, const Sched& S, const Epi& E) {
;     ...
;     for (int i = 0; i < 2; ++i) { int R, C; stage_rc(tid * 16 + i * 8192, R, C); const int Rb = (R & ~31) + perm32(R & 31);
;         voffA[i] = (unsigned)(R * g.lda + C) * 2u; voffB[i] = (unsigned)(Rb * g.ldb + C) * 2u; }
;     const size_t kstep = (size_t)(BK * 2);
;     const size_t hstepA = (size_t)HALF * g.lda * 2, hstepB = (size_t)HALF * g.ldb * 2;
;     const size_t khb = (size_t)nt * kstep;
;     const unsigned ldsw = (unsigned)wid * 1024u;
;     const int aoff = lds_byte(wr * 64 + fr, fq * 8), boff = lds_byte(wc * 32 + fr, fq * 8);
;     ...
;     f32x4 acc[2][2][4][2];
; #pragma unroll
;     for (int a = 0; a < 2; ++a)
; #pragma unroll
;         for (int b = 0; b < 2; ++b)
; #pragma unroll
;             for (int m = 0; m < 4; ++m)
; #pragma unroll
;                 for (int n = 0; n < 2; ++n) acc[a][b][m][n] = (f32x4){0.f, 0.f, 0.f, 0.f};
;     bf16x8 At[4][2], B0[2][2], B1[2][2];
;     const int one_scale = 0x7f7f7f7f;
;     i32x8 At8[4], B08[2], B18[2];
;     const char* cA = (const char*)(cur.type ? g.A2 : g.A) + (size_t)cur.pm * 2 * hstepA + (size_t)cur.kh * khb;
;     const char* cB = (const char*)(cur.type ? g.Bt2 : g.Bt) + (size_t)cur.pn * 2 * hstepB + (size_t)cur.kh * khb;
;     G_STAGE(G_SB(0, 0), cB, voffB); G_STAGE(G_SA(0, 0), cA, voffA); G_STAGE(G_SB(0, 1), cB + hstepB, voffB); G_STAGE(G_SA(0, 1), cA + hstepA, voffA);
;     if (wr == 1) G_BAR;
;     G_WAIT_V(4); G_BAR;
;     G_STAGE(G_SB(1, 0), cB + kstep, voffB); G_STAGE(G_SA(1, 0), cA + kstep, voffA); G_STAGE(G_SB(1, 1), cB + hstepB + kstep, voffB);
;     G_WAIT_V(6); G_BAR;
.LBB0_801:
	v_lshrrev_b32_e32 v20, 1, v10
	v_and_b32_e32 v20, 24, v20
	v_and_b32_e32 v19, 15, v10
	v_lshlrev_b32_e32 v21, 1, v20
	v_lshlrev_b32_e32 v10, 2, v10
	v_lshl_or_b32 v1, s1, 6, v19
	v_lshl_or_b32 v19, v19, 6, v21
	s_lshl_b32 s1, s1, 13
	v_and_b32_e32 v10, 32, v10
	v_bitop3_b32 v21, v19, s1, v10 bitop3:0xde
	s_lshl_b32 s1, s2, 5
	s_mov_b64 s[18:19], 0x80
	s_and_b32 s1, s1, 0x60
	s_add_i32 m0, s52, 0x18000
	v_lshl_add_u64 v[8:9], v[8:9], 0, s[18:19]
	s_lshl_b32 s2, s1, 7
	s_waitcnt vmcnt(4)
	s_barrier
	global_load_lds_dwordx4 v[8:9], off
	v_lshl_add_u64 v[6:7], v[6:7], 0, s[18:19]
	s_add_i32 m0, s52, 0x1a000
	s_add_i32 s56, s52, 0x8000
	s_add_i32 s57, s52, 0xa000
	global_load_lds_dwordx4 v[6:7], off
	v_lshl_add_u64 v[4:5], v[4:5], 0, s[18:19]
	s_mov_b32 m0, s56
	s_add_u32 s10, s44, 0x84080
	global_load_lds_dwordx4 v[4:5], off
	v_lshl_add_u64 v[2:3], v[2:3], 0, s[18:19]
	s_mov_b32 m0, s57
	s_addc_u32 s11, s45, 0
	global_load_lds_dwordx4 v[2:3], off
	s_add_i32 m0, s52, 0x1c000
	v_lshl_add_u64 v[2:3], s[10:11], 0, v[148:149]
	global_load_lds_dwordx4 v[2:3], off
	v_lshl_add_u64 v[2:3], s[10:11], 0, v[152:153]
	s_add_i32 m0, s52, 0x1e000
	v_or_b32_e32 v173, s1, v20
	global_load_lds_dwordx4 v[2:3], off
	v_lshrrev_b32_e32 v3, 1, v11
	v_mul_lo_u32 v2, v13, s0
	s_mov_b32 s1, 0x8400
	v_mad_u64_u32 v[2:3], s[10:11], v3, s1, v[2:3]
	v_or_b32_e32 v2, v2, v12
	s_sext_i32_i8 s66, s3
	v_bitop3_b32 v172, v19, s2, v10 bitop3:0xde
	s_mov_b64 s[2:3], 0x84080
	v_add_lshl_u32 v2, v2, v14, 1
	v_mov_b32_e32 v3, v149
	v_lshl_add_u64 v[154:155], v[2:3], 0, s[2:3]
	v_lshrrev_b32_e32 v3, 1, v15
	v_mul_lo_u32 v2, v16, s0
	v_mad_u64_u32 v[2:3], s[0:1], v3, s1, v[2:3]
	s_waitcnt vmcnt(6)
	v_or_b32_e32 v2, v2, v17
	v_add_lshl_u32 v2, v2, v18, 1
	v_mov_b32_e32 v3, v149
	v_lshl_add_u64 v[156:157], v[2:3], 0, s[2:3]
	s_add_i32 s58, 0, 0x10000
	v_add_u32_e32 v174, 0, v21
	s_add_i32 s59, 0, 0x14000
	s_movk_i32 s60, 0x1080
	s_mov_b32 s61, 0
	v_mov_b32_e32 v2, v149
	v_mov_b32_e32 v4, v149
	v_mov_b32_e32 v5, v149
	v_mov_b32_e32 v6, v149
	v_mov_b32_e32 v7, v149
	v_mov_b32_e32 v8, v149
	v_mov_b32_e32 v9, v149
	v_mov_b32_e32 v10, v149
	v_mov_b32_e32 v11, v149
	v_mov_b32_e32 v12, v149
	v_mov_b32_e32 v13, v149
	v_mov_b32_e32 v14, v149
	v_mov_b32_e32 v15, v149
	v_mov_b32_e32 v16, v149
	v_mov_b32_e32 v17, v149
	v_mov_b32_e32 v18, v149
	v_mov_b32_e32 v19, v149
	v_mov_b32_e32 v20, v149
	v_mov_b32_e32 v21, v149
	s_waitcnt vmcnt(0)
	v_mov_b32_e32 v22, v149
	v_mov_b32_e32 v23, v149
	v_mov_b64_e32 v[24:25], v[22:23]
	v_mov_b64_e32 v[26:27], v[22:23]
	v_mov_b64_e32 v[28:29], v[22:23]
	v_mov_b64_e32 v[30:31], v[22:23]
	v_mov_b64_e32 v[32:33], v[22:23]
	v_mov_b64_e32 v[34:35], v[22:23]
	v_mov_b64_e32 v[36:37], v[22:23]
	v_mov_b64_e32 v[38:39], v[22:23]
	v_mov_b64_e32 v[40:41], v[22:23]
	v_mov_b64_e32 v[42:43], v[22:23]
	v_mov_b64_e32 v[44:45], v[22:23]
	v_mov_b64_e32 v[46:47], v[22:23]
	v_mov_b64_e32 v[48:49], v[22:23]
	v_mov_b64_e32 v[50:51], v[22:23]
	v_mov_b64_e32 v[52:53], v[22:23]
	v_mov_b64_e32 v[54:55], v[22:23]
	v_mov_b64_e32 v[56:57], v[22:23]
	v_mov_b64_e32 v[58:59], v[22:23]
	v_mov_b64_e32 v[60:61], v[22:23]
	v_mov_b64_e32 v[62:63], v[22:23]
	v_mov_b64_e32 v[64:65], v[22:23]
	v_mov_b64_e32 v[66:67], v[22:23]
	v_mov_b64_e32 v[68:69], v[22:23]
	v_mov_b64_e32 v[70:71], v[22:23]
	v_mov_b64_e32 v[72:73], v[22:23]
	v_mov_b64_e32 v[74:75], v[22:23]
	v_mov_b64_e32 v[76:77], v[22:23]
	v_mov_b64_e32 v[78:79], v[22:23]
	v_mov_b64_e32 v[80:81], v[22:23]
	v_mov_b64_e32 v[82:83], v[22:23]
	v_mov_b64_e32 v[84:85], v[22:23]
	v_mov_b64_e32 v[86:87], v[22:23]
	v_mov_b64_e32 v[88:89], v[22:23]
	v_mov_b64_e32 v[90:91], v[22:23]
	v_mov_b64_e32 v[92:93], v[22:23]
	v_mov_b64_e32 v[94:95], v[22:23]
	v_mov_b64_e32 v[96:97], v[22:23]
	v_mov_b64_e32 v[98:99], v[22:23]
	v_mov_b64_e32 v[100:101], v[22:23]
	v_mov_b64_e32 v[102:103], v[22:23]
	v_mov_b64_e32 v[104:105], v[22:23]
	v_mov_b64_e32 v[106:107], v[22:23]
	v_mov_b64_e32 v[108:109], v[22:23]
	v_mov_b64_e32 v[110:111], v[22:23]
	v_mov_b64_e32 v[112:113], v[22:23]
	v_mov_b64_e32 v[114:115], v[22:23]
	v_mov_b64_e32 v[116:117], v[22:23]
	v_mov_b64_e32 v[118:119], v[22:23]
	v_mov_b64_e32 v[120:121], v[22:23]
	v_mov_b64_e32 v[122:123], v[22:23]
	v_mov_b64_e32 v[124:125], v[22:23]
	v_mov_b64_e32 v[126:127], v[22:23]
	v_mov_b64_e32 v[128:129], v[22:23]
	s_barrier
	s_branch .LBB0_804

; template <int MODE  , class Epi, class Sched>
; __device__ __forceinline__ void gemm_phase(LAS unsigned char* lds, const GemmDesc g, const Sched& S, const Epi& E) {
;     ...
;         if (zero) {
; #pragma unroll
;             for (int a = 0; a < 2; ++a)
; #pragma unroll
;                 for (int b = 0; b < 2; ++b)
; #pragma unroll
;                     for (int m = 0; m < 4; ++m)
; #pragma unroll
;                         for (int n = 0; n < 2; ++n) acc[a][b][m][n] = (f32x4){0.f, 0.f, 0.f, 0.f};
;         }
.LBB0_818:
	s_mov_b64 s[44:45], -1
	s_and_b64 vcc, exec, s[40:41]
	s_cbranch_vccz .LBB0_803
	s_andn2_b64 vcc, exec, s[42:43]
	s_cbranch_vccnz .LBB0_802
	v_mov_b32_e32 v2, 0
	v_mov_b32_e32 v3, v2
	v_mov_b64_e32 v[4:5], v[2:3]
	v_mov_b64_e32 v[6:7], v[2:3]
	v_mov_b64_e32 v[8:9], v[2:3]
	v_mov_b64_e32 v[10:11], v[2:3]
	v_mov_b64_e32 v[12:13], v[2:3]
	v_mov_b64_e32 v[14:15], v[2:3]
	v_mov_b64_e32 v[16:17], v[2:3]
	v_mov_b64_e32 v[18:19], v[2:3]
	v_mov_b64_e32 v[20:21], v[2:3]
	v_mov_b64_e32 v[22:23], v[2:3]
	v_mov_b64_e32 v[24:25], v[2:3]
	v_mov_b64_e32 v[26:27], v[2:3]
	v_mov_b64_e32 v[28:29], v[2:3]
	v_mov_b64_e32 v[30:31], v[2:3]
	v_mov_b64_e32 v[32:33], v[2:3]
	v_mov_b64_e32 v[34:35], v[2:3]
	v_mov_b64_e32 v[36:37], v[2:3]
	v_mov_b64_e32 v[38:39], v[2:3]
	v_mov_b64_e32 v[40:41], v[2:3]
	v_mov_b64_e32 v[42:43], v[2:3]
	v_mov_b64_e32 v[44:45], v[2:3]
	v_mov_b64_e32 v[46:47], v[2:3]
	v_mov_b64_e32 v[48:49], v[2:3]
	v_mov_b64_e32 v[50:51], v[2:3]
	v_mov_b64_e32 v[52:53], v[2:3]
	v_mov_b64_e32 v[54:55], v[2:3]
	v_mov_b64_e32 v[56:57], v[2:3]
	v_mov_b64_e32 v[58:59], v[2:3]
	v_mov_b64_e32 v[60:61], v[2:3]
	v_mov_b64_e32 v[62:63], v[2:3]
	v_mov_b64_e32 v[64:65], v[2:3]
	v_mov_b64_e32 v[66:67], v[2:3]
	v_mov_b64_e32 v[68:69], v[2:3]
	v_mov_b64_e32 v[70:71], v[2:3]
	v_mov_b64_e32 v[72:73], v[2:3]
	v_mov_b64_e32 v[74:75], v[2:3]
	v_mov_b64_e32 v[76:77], v[2:3]
	v_mov_b64_e32 v[78:79], v[2:3]
	v_mov_b64_e32 v[80:81], v[2:3]
	v_mov_b64_e32 v[82:83], v[2:3]
	v_mov_b64_e32 v[84:85], v[2:3]
	v_mov_b64_e32 v[86:87], v[2:3]
	v_mov_b64_e32 v[88:89], v[2:3]
	v_mov_b64_e32 v[90:91], v[2:3]
	v_mov_b64_e32 v[92:93], v[2:3]
	v_mov_b64_e32 v[94:95], v[2:3]
	v_mov_b64_e32 v[96:97], v[2:3]
	v_mov_b64_e32 v[98:99], v[2:3]
	v_mov_b64_e32 v[100:101], v[2:3]
	v_mov_b64_e32 v[102:103], v[2:3]
	v_mov_b64_e32 v[104:105], v[2:3]
	v_mov_b64_e32 v[106:107], v[2:3]
	v_mov_b64_e32 v[108:109], v[2:3]
	v_mov_b64_e32 v[110:111], v[2:3]
	v_mov_b64_e32 v[112:113], v[2:3]
	v_mov_b64_e32 v[114:115], v[2:3]
	v_mov_b64_e32 v[116:117], v[2:3]
	v_mov_b64_e32 v[118:119], v[2:3]
	v_mov_b64_e32 v[120:121], v[2:3]
	v_mov_b64_e32 v[122:123], v[2:3]
	v_mov_b64_e32 v[124:125], v[2:3]
	v_mov_b64_e32 v[126:127], v[2:3]
	v_mov_b64_e32 v[128:129], v[2:3]
	s_branch .LBB0_802

; #define G_STAGE(bufoff, gbase, voff) do { _Pragma("unroll") for (int _i = 0; _i < 2; ++_i) \
;         __builtin_amdgcn_global_load_lds((const unsigned*)((const char*)(gbase) + (voff)[_i]), (LAS unsigned*)(lds + (bufoff) + ldsw + _i * 8192), 16, 0, 0); } while (0)
; #define G_WAIT_V(n) asm volatile("s_waitcnt vmcnt(" #n ")" ::: "memory")
; #define G_BAR __builtin_amdgcn_s_barrier()
; template <int MODE  , class Epi, class Sched>
; __device__ __forceinline__ void gemm_phase(LAS unsigned char* lds, const GemmDesc g, const Sched& S, const Epi& E) {
;     ...
;     for (int i = 0; i < 2; ++i) { int R, C; stage_rc(tid * 16 + i * 8192, R, C); const int Rb = (R & ~31) + perm32(R & 31);
;         voffA[i] = (unsigned)(R * g.lda + C) * 2u; voffB[i] = (unsigned)(Rb * g.ldb + C) * 2u; }
;     const size_t kstep = (size_t)(BK * 2);
;     const size_t hstepA = (size_t)HALF * g.lda * 2, hstepB = (size_t)HALF * g.ldb * 2;
;     const size_t khb = (size_t)nt * kstep;
;     const unsigned ldsw = (unsigned)wid * 1024u;
;     const int aoff = lds_byte(wr * 64 + fr, fq * 8), boff = lds_byte(wc * 32 + fr, fq * 8);
;     ...
;     f32x4 acc[2][2][4][2];
; #pragma unroll
;     for (int a = 0; a < 2; ++a)
; #pragma unroll
;         for (int b = 0; b < 2; ++b)
; #pragma unroll
;             for (int m = 0; m < 4; ++m)
; #pragma unroll
;                 for (int n = 0; n < 2; ++n) acc[a][b][m][n] = (f32x4){0.f, 0.f, 0.f, 0.f};
;     bf16x8 At[4][2], B0[2][2], B1[2][2];
;     const int one_scale = 0x7f7f7f7f;
;     i32x8 At8[4], B08[2], B18[2];
;     const char* cA = (const char*)(cur.type ? g.A2 : g.A) + (size_t)cur.pm * 2 * hstepA + (size_t)cur.kh * khb;
;     const char* cB = (const char*)(cur.type ? g.Bt2 : g.Bt) + (size_t)cur.pn * 2 * hstepB + (size_t)cur.kh * khb;
;     G_STAGE(G_SB(0, 0), cB, voffB); G_STAGE(G_SA(0, 0), cA, voffA); G_STAGE(G_SB(0, 1), cB + hstepB, voffB); G_STAGE(G_SA(0, 1), cA + hstepA, voffA);
;     if (wr == 1) G_BAR;
;     G_WAIT_V(4); G_BAR;
;     G_STAGE(G_SB(1, 0), cB + kstep, voffB); G_STAGE(G_SA(1, 0), cA + kstep, voffA); G_STAGE(G_SB(1, 1), cB + hstepB + kstep, voffB);
;     G_WAIT_V(6); G_BAR;
.LBB0_883:
	v_lshrrev_b32_e32 v20, 1, v10
	v_and_b32_e32 v20, 24, v20
	v_and_b32_e32 v19, 15, v10
	v_lshlrev_b32_e32 v21, 1, v20
	v_lshlrev_b32_e32 v10, 2, v10
	v_lshl_or_b32 v1, s1, 6, v19
	v_lshl_or_b32 v19, v19, 6, v21
	s_lshl_b32 s1, s1, 13
	v_and_b32_e32 v10, 32, v10
	v_bitop3_b32 v21, v19, s1, v10 bitop3:0xde
	s_lshl_b32 s1, s10, 5
	s_mov_b64 s[16:17], 0x80
	s_and_b32 s1, s1, 0x60
	s_add_i32 m0, s50, 0x18000
	v_lshl_add_u64 v[8:9], v[8:9], 0, s[16:17]
	s_lshl_b32 s2, s1, 7
	s_waitcnt vmcnt(4)
	s_barrier
	global_load_lds_dwordx4 v[8:9], off
	v_lshl_add_u64 v[6:7], v[6:7], 0, s[16:17]
	s_add_i32 m0, s50, 0x1a000
	s_add_i32 s54, s50, 0x8000
	s_add_i32 s55, s50, 0xa000
	global_load_lds_dwordx4 v[6:7], off
	v_lshl_add_u64 v[4:5], v[4:5], 0, s[16:17]
	s_mov_b32 m0, s54
	s_add_u32 s10, s42, 0x84080
	global_load_lds_dwordx4 v[4:5], off
	v_lshl_add_u64 v[2:3], v[2:3], 0, s[16:17]
	s_mov_b32 m0, s55
	s_addc_u32 s11, s43, 0
	global_load_lds_dwordx4 v[2:3], off
	s_add_i32 m0, s50, 0x1c000
	v_lshl_add_u64 v[2:3], s[10:11], 0, v[148:149]
	global_load_lds_dwordx4 v[2:3], off
	v_lshl_add_u64 v[2:3], s[10:11], 0, v[152:153]
	s_add_i32 m0, s50, 0x1e000
	v_or_b32_e32 v175, s1, v20
	global_load_lds_dwordx4 v[2:3], off
	v_lshrrev_b32_e32 v3, 1, v11
	v_mul_lo_u32 v2, v13, s0
	s_mov_b32 s1, 0x8400
	v_mad_u64_u32 v[2:3], s[10:11], v3, s1, v[2:3]
	v_or_b32_e32 v2, v2, v12
	v_bitop3_b32 v174, v19, s2, v10 bitop3:0xde
	s_mov_b64 s[2:3], 0x84080
	v_add_lshl_u32 v2, v2, v14, 1
	v_mov_b32_e32 v3, v149
	v_lshl_add_u64 v[154:155], v[2:3], 0, s[2:3]
	v_lshrrev_b32_e32 v3, 1, v15
	v_mul_lo_u32 v2, v16, s0
	v_mad_u64_u32 v[2:3], s[0:1], v3, s1, v[2:3]
	s_waitcnt vmcnt(6)
	v_or_b32_e32 v2, v2, v17
	v_add_lshl_u32 v2, v2, v18, 1
	v_mov_b32_e32 v3, v149
	v_lshl_add_u64 v[156:157], v[2:3], 0, s[2:3]
	s_movk_i32 s56, 0x79
	s_add_i32 s57, 0, 0x10000
	v_add_u32_e32 v176, 0, v21
	s_add_i32 s58, 0, 0x14000
	s_movk_i32 s59, 0x1080
	s_mov_b32 s60, 0
	v_mov_b32_e32 v2, v149
	v_mov_b32_e32 v4, v149
	v_mov_b32_e32 v5, v149
	v_mov_b32_e32 v6, v149
	v_mov_b32_e32 v7, v149
	v_mov_b32_e32 v8, v149
	v_mov_b32_e32 v9, v149
	v_mov_b32_e32 v10, v149
	v_mov_b32_e32 v11, v149
	v_mov_b32_e32 v12, v149
	v_mov_b32_e32 v13, v149
	v_mov_b32_e32 v14, v149
	v_mov_b32_e32 v15, v149
	v_mov_b32_e32 v16, v149
	v_mov_b32_e32 v17, v149
	v_mov_b32_e32 v18, v149
	v_mov_b32_e32 v19, v149
	v_mov_b32_e32 v20, v149
	v_mov_b32_e32 v21, v149
	s_waitcnt vmcnt(0)
	v_mov_b32_e32 v22, v149
	v_mov_b32_e32 v23, v149
	v_mov_b64_e32 v[24:25], v[22:23]
	v_mov_b64_e32 v[26:27], v[22:23]
	v_mov_b64_e32 v[28:29], v[22:23]
	v_mov_b64_e32 v[30:31], v[22:23]
	v_mov_b64_e32 v[32:33], v[22:23]
	v_mov_b64_e32 v[34:35], v[22:23]
	v_mov_b64_e32 v[36:37], v[22:23]
	v_mov_b64_e32 v[38:39], v[22:23]
	v_mov_b64_e32 v[40:41], v[22:23]
	v_mov_b64_e32 v[42:43], v[22:23]
	v_mov_b64_e32 v[44:45], v[22:23]
	v_mov_b64_e32 v[46:47], v[22:23]
	v_mov_b64_e32 v[48:49], v[22:23]
	v_mov_b64_e32 v[50:51], v[22:23]
	v_mov_b64_e32 v[52:53], v[22:23]
	v_mov_b64_e32 v[54:55], v[22:23]
	v_mov_b64_e32 v[56:57], v[22:23]
	v_mov_b64_e32 v[58:59], v[22:23]
	v_mov_b64_e32 v[60:61], v[22:23]
	v_mov_b64_e32 v[62:63], v[22:23]
	v_mov_b64_e32 v[64:65], v[22:23]
	v_mov_b64_e32 v[66:67], v[22:23]
	v_mov_b64_e32 v[68:69], v[22:23]
	v_mov_b64_e32 v[70:71], v[22:23]
	v_mov_b64_e32 v[72:73], v[22:23]
	v_mov_b64_e32 v[74:75], v[22:23]
	v_mov_b64_e32 v[76:77], v[22:23]
	v_mov_b64_e32 v[78:79], v[22:23]
	v_mov_b64_e32 v[80:81], v[22:23]
	v_mov_b64_e32 v[82:83], v[22:23]
	v_mov_b64_e32 v[84:85], v[22:23]
	v_mov_b64_e32 v[86:87], v[22:23]
	v_mov_b64_e32 v[88:89], v[22:23]
	v_mov_b64_e32 v[90:91], v[22:23]
	v_mov_b64_e32 v[92:93], v[22:23]
	v_mov_b64_e32 v[94:95], v[22:23]
	v_mov_b64_e32 v[96:97], v[22:23]
	v_mov_b64_e32 v[98:99], v[22:23]
	v_mov_b64_e32 v[100:101], v[22:23]
	v_mov_b64_e32 v[102:103], v[22:23]
	v_mov_b64_e32 v[104:105], v[22:23]
	v_mov_b64_e32 v[106:107], v[22:23]
	v_mov_b64_e32 v[108:109], v[22:23]
	v_mov_b64_e32 v[110:111], v[22:23]
	v_mov_b64_e32 v[112:113], v[22:23]
	v_mov_b64_e32 v[114:115], v[22:23]
	v_mov_b64_e32 v[116:117], v[22:23]
	v_mov_b64_e32 v[118:119], v[22:23]
	v_mov_b64_e32 v[120:121], v[22:23]
	v_mov_b64_e32 v[122:123], v[22:23]
	v_mov_b64_e32 v[124:125], v[22:23]
	v_mov_b64_e32 v[126:127], v[22:23]
	v_mov_b64_e32 v[128:129], v[22:23]
	s_barrier
	s_branch .LBB0_886

; template <int MODE  , class Epi, class Sched>
; __device__ __forceinline__ void gemm_phase(LAS unsigned char* lds, const GemmDesc g, const Sched& S, const Epi& E) {
;     ...
;         if (zero) {
; #pragma unroll
;             for (int a = 0; a < 2; ++a)
; #pragma unroll
;                 for (int b = 0; b < 2; ++b)
; #pragma unroll
;                     for (int m = 0; m < 4; ++m)
; #pragma unroll
;                         for (int n = 0; n < 2; ++n) acc[a][b][m][n] = (f32x4){0.f, 0.f, 0.f, 0.f};
;         }
.LBB0_909:
	s_andn2_b64 vcc, exec, s[42:43]
	s_cbranch_vccnz .LBB0_884
	v_mov_b32_e32 v2, 0
	v_mov_b32_e32 v3, v2
	v_mov_b64_e32 v[4:5], v[2:3]
	v_mov_b64_e32 v[6:7], v[2:3]
	v_mov_b64_e32 v[8:9], v[2:3]
	v_mov_b64_e32 v[10:11], v[2:3]
	v_mov_b64_e32 v[12:13], v[2:3]
	v_mov_b64_e32 v[14:15], v[2:3]
	v_mov_b64_e32 v[16:17], v[2:3]
	v_mov_b64_e32 v[18:19], v[2:3]
	v_mov_b64_e32 v[20:21], v[2:3]
	v_mov_b64_e32 v[22:23], v[2:3]
	v_mov_b64_e32 v[24:25], v[2:3]
	v_mov_b64_e32 v[26:27], v[2:3]
	v_mov_b64_e32 v[28:29], v[2:3]
	v_mov_b64_e32 v[30:31], v[2:3]
	v_mov_b64_e32 v[32:33], v[2:3]
	v_mov_b64_e32 v[34:35], v[2:3]
	v_mov_b64_e32 v[36:37], v[2:3]
	v_mov_b64_e32 v[38:39], v[2:3]
	v_mov_b64_e32 v[40:41], v[2:3]
	v_mov_b64_e32 v[42:43], v[2:3]
	v_mov_b64_e32 v[44:45], v[2:3]
	v_mov_b64_e32 v[46:47], v[2:3]
	v_mov_b64_e32 v[48:49], v[2:3]
	v_mov_b64_e32 v[50:51], v[2:3]
	v_mov_b64_e32 v[52:53], v[2:3]
	v_mov_b64_e32 v[54:55], v[2:3]
	v_mov_b64_e32 v[56:57], v[2:3]
	v_mov_b64_e32 v[58:59], v[2:3]
	v_mov_b64_e32 v[60:61], v[2:3]
	v_mov_b64_e32 v[62:63], v[2:3]
	v_mov_b64_e32 v[64:65], v[2:3]
	v_mov_b64_e32 v[66:67], v[2:3]
	v_mov_b64_e32 v[68:69], v[2:3]
	v_mov_b64_e32 v[70:71], v[2:3]
	v_mov_b64_e32 v[72:73], v[2:3]
	v_mov_b64_e32 v[74:75], v[2:3]
	v_mov_b64_e32 v[76:77], v[2:3]
	v_mov_b64_e32 v[78:79], v[2:3]
	v_mov_b64_e32 v[80:81], v[2:3]
	v_mov_b64_e32 v[82:83], v[2:3]
	v_mov_b64_e32 v[84:85], v[2:3]
	v_mov_b64_e32 v[86:87], v[2:3]
	v_mov_b64_e32 v[88:89], v[2:3]
	v_mov_b64_e32 v[90:91], v[2:3]
	v_mov_b64_e32 v[92:93], v[2:3]
	v_mov_b64_e32 v[94:95], v[2:3]
	v_mov_b64_e32 v[96:97], v[2:3]
	v_mov_b64_e32 v[98:99], v[2:3]
	v_mov_b64_e32 v[100:101], v[2:3]
	v_mov_b64_e32 v[102:103], v[2:3]
	v_mov_b64_e32 v[104:105], v[2:3]
	v_mov_b64_e32 v[106:107], v[2:3]
	v_mov_b64_e32 v[108:109], v[2:3]
	v_mov_b64_e32 v[110:111], v[2:3]
	v_mov_b64_e32 v[112:113], v[2:3]
	v_mov_b64_e32 v[114:115], v[2:3]
	v_mov_b64_e32 v[116:117], v[2:3]
	v_mov_b64_e32 v[118:119], v[2:3]
	v_mov_b64_e32 v[120:121], v[2:3]
	v_mov_b64_e32 v[122:123], v[2:3]
	v_mov_b64_e32 v[124:125], v[2:3]
	v_mov_b64_e32 v[126:127], v[2:3]
	v_mov_b64_e32 v[128:129], v[2:3]
	s_branch .LBB0_884

; #define G_STAGE(bufoff, gbase, voff) do { _Pragma("unroll") for (int _i = 0; _i < 2; ++_i) \
;         __builtin_amdgcn_global_load_lds((const unsigned*)((const char*)(gbase) + (voff)[_i]), (LAS unsigned*)(lds + (bufoff) + ldsw + _i * 8192), 16, 0, 0); } while (0)
; #define G_WAIT_V(n) asm volatile("s_waitcnt vmcnt(" #n ")" ::: "memory")
; #define G_BAR __builtin_amdgcn_s_barrier()
; template <int MODE  , class Epi, class Sched>
; __device__ __forceinline__ void gemm_phase(LAS unsigned char* lds, const GemmDesc g, const Sched& S, const Epi& E) {
;     ...
;     for (int i = 0; i < 2; ++i) { int R, C; stage_rc(tid * 16 + i * 8192, R, C); const int Rb = (R & ~31) + perm32(R & 31);
;         voffA[i] = (unsigned)(R * g.lda + C) * 2u; voffB[i] = (unsigned)(Rb * g.ldb + C) * 2u; }
;     const size_t kstep = (size_t)(BK * 2);
;     const size_t hstepA = (size_t)HALF * g.lda * 2, hstepB = (size_t)HALF * g.ldb * 2;
;     const size_t khb = (size_t)nt * kstep;
;     const unsigned ldsw = (unsigned)wid * 1024u;
;     const int aoff = lds_byte(wr * 64 + fr, fq * 8), boff = lds_byte(wc * 32 + fr, fq * 8);
;     ...
;     f32x4 acc[2][2][4][2];
; #pragma unroll
;     for (int a = 0; a < 2; ++a)
; #pragma unroll
;         for (int b = 0; b < 2; ++b)
; #pragma unroll
;             for (int m = 0; m < 4; ++m)
; #pragma unroll
;                 for (int n = 0; n < 2; ++n) acc[a][b][m][n] = (f32x4){0.f, 0.f, 0.f, 0.f};
;     bf16x8 At[4][2], B0[2][2], B1[2][2];
;     const int one_scale = 0x7f7f7f7f;
;     i32x8 At8[4], B08[2], B18[2];
;     const char* cA = (const char*)(cur.type ? g.A2 : g.A) + (size_t)cur.pm * 2 * hstepA + (size_t)cur.kh * khb;
;     const char* cB = (const char*)(cur.type ? g.Bt2 : g.Bt) + (size_t)cur.pn * 2 * hstepB + (size_t)cur.kh * khb;
;     G_STAGE(G_SB(0, 0), cB, voffB); G_STAGE(G_SA(0, 0), cA, voffA); G_STAGE(G_SB(0, 1), cB + hstepB, voffB); G_STAGE(G_SA(0, 1), cA + hstepA, voffA);
;     if (wr == 1) G_BAR;
;     G_WAIT_V(4); G_BAR;
;     G_STAGE(G_SB(1, 0), cB + kstep, voffB); G_STAGE(G_SA(1, 0), cA + kstep, voffA); G_STAGE(G_SB(1, 1), cB + hstepB + kstep, voffB);
;     G_WAIT_V(6); G_BAR;
.LBB0_973:
	v_lshrrev_b32_e32 v20, 1, v10
	v_and_b32_e32 v20, 24, v20
	v_and_b32_e32 v19, 15, v10
	v_lshlrev_b32_e32 v21, 1, v20
	v_lshlrev_b32_e32 v10, 2, v10
	v_lshl_or_b32 v1, s1, 6, v19
	v_lshl_or_b32 v19, v19, 6, v21
	s_lshl_b32 s1, s1, 13
	v_and_b32_e32 v10, 32, v10
	v_bitop3_b32 v21, v19, s1, v10 bitop3:0xde
	s_lshl_b32 s1, s2, 5
	s_mov_b64 s[4:5], 0x80
	s_and_b32 s1, s1, 0x60
	s_add_i32 m0, s44, 0x18000
	v_lshl_add_u64 v[8:9], v[8:9], 0, s[4:5]
	s_lshl_b32 s2, s1, 7
	s_waitcnt vmcnt(4)
	s_barrier
	global_load_lds_dwordx4 v[8:9], off
	v_lshl_add_u64 v[6:7], v[6:7], 0, s[4:5]
	s_add_i32 m0, s44, 0x1a000
	s_add_i32 s48, s44, 0x8000
	s_add_i32 s49, s44, 0xa000
	global_load_lds_dwordx4 v[6:7], off
	v_lshl_add_u64 v[4:5], v[4:5], 0, s[4:5]
	s_mov_b32 m0, s48
	s_add_u32 s10, s34, 0x84080
	global_load_lds_dwordx4 v[4:5], off
	v_lshl_add_u64 v[2:3], v[2:3], 0, s[4:5]
	s_mov_b32 m0, s49
	s_addc_u32 s11, s35, 0
	global_load_lds_dwordx4 v[2:3], off
	s_add_i32 m0, s44, 0x1c000
	v_lshl_add_u64 v[2:3], s[10:11], 0, v[132:133]
	global_load_lds_dwordx4 v[2:3], off
	v_lshl_add_u64 v[2:3], s[10:11], 0, v[136:137]
	s_add_i32 m0, s44, 0x1e000
	v_or_b32_e32 v143, s1, v20
	global_load_lds_dwordx4 v[2:3], off
	v_lshrrev_b32_e32 v3, 1, v11
	v_mul_lo_u32 v2, v13, s0
	s_mov_b32 s1, 0x8400
	v_mad_u64_u32 v[2:3], s[10:11], v3, s1, v[2:3]
	v_or_b32_e32 v2, v2, v12
	s_sext_i32_i8 s58, s3
	v_bitop3_b32 v142, v19, s2, v10 bitop3:0xde
	s_mov_b64 s[2:3], 0x84080
	v_add_lshl_u32 v2, v2, v14, 1
	v_mov_b32_e32 v3, v133
	v_lshl_add_u64 v[138:139], v[2:3], 0, s[2:3]
	v_lshrrev_b32_e32 v3, 1, v15
	v_mul_lo_u32 v2, v16, s0
	v_mad_u64_u32 v[2:3], s[0:1], v3, s1, v[2:3]
	s_waitcnt vmcnt(6)
	v_or_b32_e32 v2, v2, v17
	v_add_lshl_u32 v2, v2, v18, 1
	v_mov_b32_e32 v3, v133
	v_lshl_add_u64 v[140:141], v[2:3], 0, s[2:3]
	s_add_i32 s50, 0, 0x10000
	v_add_u32_e32 v144, 0, v21
	s_add_i32 s51, 0, 0x14000
	s_movk_i32 s52, 0x1080
	s_mov_b32 s53, 0
	v_mov_b32_e32 v4, v133
	v_mov_b32_e32 v5, v133
	v_mov_b32_e32 v2, v133
	v_mov_b64_e32 v[6:7], v[4:5]
	v_mov_b64_e32 v[8:9], v[4:5]
	v_mov_b64_e32 v[10:11], v[4:5]
	v_mov_b64_e32 v[12:13], v[4:5]
	v_mov_b64_e32 v[14:15], v[4:5]
	v_mov_b64_e32 v[16:17], v[4:5]
	v_mov_b64_e32 v[18:19], v[4:5]
	v_mov_b64_e32 v[20:21], v[4:5]
	v_mov_b64_e32 v[22:23], v[4:5]
	v_mov_b64_e32 v[24:25], v[4:5]
	v_mov_b64_e32 v[26:27], v[4:5]
	v_mov_b64_e32 v[28:29], v[4:5]
	v_mov_b64_e32 v[30:31], v[4:5]
	v_mov_b64_e32 v[32:33], v[4:5]
	v_mov_b64_e32 v[34:35], v[4:5]
	v_mov_b64_e32 v[36:37], v[4:5]
	v_mov_b64_e32 v[38:39], v[4:5]
	v_mov_b64_e32 v[40:41], v[4:5]
	v_mov_b64_e32 v[42:43], v[4:5]
	v_mov_b64_e32 v[44:45], v[4:5]
	v_mov_b64_e32 v[46:47], v[4:5]
	v_mov_b64_e32 v[48:49], v[4:5]
	v_mov_b64_e32 v[50:51], v[4:5]
	v_mov_b64_e32 v[52:53], v[4:5]
	v_mov_b64_e32 v[54:55], v[4:5]
	v_mov_b64_e32 v[56:57], v[4:5]
	v_mov_b64_e32 v[58:59], v[4:5]
	v_mov_b64_e32 v[60:61], v[4:5]
	v_mov_b64_e32 v[62:63], v[4:5]
	v_mov_b64_e32 v[64:65], v[4:5]
	v_mov_b64_e32 v[66:67], v[4:5]
	v_mov_b64_e32 v[68:69], v[4:5]
	v_mov_b64_e32 v[70:71], v[4:5]
	v_mov_b64_e32 v[72:73], v[4:5]
	v_mov_b64_e32 v[74:75], v[4:5]
	v_mov_b64_e32 v[76:77], v[4:5]
	v_mov_b64_e32 v[78:79], v[4:5]
	v_mov_b64_e32 v[80:81], v[4:5]
	v_mov_b64_e32 v[82:83], v[4:5]
	v_mov_b64_e32 v[84:85], v[4:5]
	v_mov_b64_e32 v[86:87], v[4:5]
	v_mov_b64_e32 v[88:89], v[4:5]
	v_mov_b64_e32 v[90:91], v[4:5]
	v_mov_b64_e32 v[92:93], v[4:5]
	v_mov_b64_e32 v[94:95], v[4:5]
	v_mov_b64_e32 v[96:97], v[4:5]
	v_mov_b64_e32 v[98:99], v[4:5]
	v_mov_b64_e32 v[100:101], v[4:5]
	v_mov_b64_e32 v[102:103], v[4:5]
	v_mov_b64_e32 v[104:105], v[4:5]
	v_mov_b64_e32 v[106:107], v[4:5]
	v_mov_b64_e32 v[108:109], v[4:5]
	v_mov_b64_e32 v[110:111], v[4:5]
	v_mov_b64_e32 v[112:113], v[4:5]
	v_mov_b64_e32 v[114:115], v[4:5]
	v_mov_b64_e32 v[116:117], v[4:5]
	v_mov_b64_e32 v[118:119], v[4:5]
	v_mov_b64_e32 v[120:121], v[4:5]
	v_mov_b64_e32 v[122:123], v[4:5]
	v_mov_b64_e32 v[124:125], v[4:5]
	v_mov_b64_e32 v[126:127], v[4:5]
	v_mov_b64_e32 v[128:129], v[4:5]
	s_barrier
	s_branch .LBB0_976

; template <int MODE  , class Epi, class Sched>
; __device__ __forceinline__ void gemm_phase(LAS unsigned char* lds, const GemmDesc g, const Sched& S, const Epi& E) {
;     ...
;         if (!has_next) break;
;         if (zero) {
; #pragma unroll
;             for (int a = 0; a < 2; ++a)
; #pragma unroll
;                 for (int b = 0; b < 2; ++b)
; #pragma unroll
;                     for (int m = 0; m < 4; ++m)
; #pragma unroll
;                         for (int n = 0; n < 2; ++n) acc[a][b][m][n] = (f32x4){0.f, 0.f, 0.f, 0.f};
;         }
.LBB0_990:
	s_mov_b64 s[20:21], -1
	s_and_b64 vcc, exec, s[18:19]
	s_cbranch_vccz .LBB0_975
	s_andn2_b64 vcc, exec, s[34:35]
	s_cbranch_vccnz .LBB0_974
	v_mov_b32_e32 v2, 0
	v_mov_b32_e32 v3, v2
	v_mov_b64_e32 v[4:5], v[2:3]
	v_mov_b64_e32 v[6:7], v[2:3]
	v_mov_b64_e32 v[8:9], v[2:3]
	v_mov_b64_e32 v[10:11], v[2:3]
	v_mov_b64_e32 v[12:13], v[2:3]
	v_mov_b64_e32 v[14:15], v[2:3]
	v_mov_b64_e32 v[16:17], v[2:3]
	v_mov_b64_e32 v[18:19], v[2:3]
	v_mov_b64_e32 v[20:21], v[2:3]
	v_mov_b64_e32 v[22:23], v[2:3]
	v_mov_b64_e32 v[24:25], v[2:3]
	v_mov_b64_e32 v[26:27], v[2:3]
	v_mov_b64_e32 v[28:29], v[2:3]
	v_mov_b64_e32 v[30:31], v[2:3]
	v_mov_b64_e32 v[32:33], v[2:3]
	v_mov_b64_e32 v[34:35], v[2:3]
	v_mov_b64_e32 v[36:37], v[2:3]
	v_mov_b64_e32 v[38:39], v[2:3]
	v_mov_b64_e32 v[40:41], v[2:3]
	v_mov_b64_e32 v[42:43], v[2:3]
	v_mov_b64_e32 v[44:45], v[2:3]
	v_mov_b64_e32 v[46:47], v[2:3]
	v_mov_b64_e32 v[48:49], v[2:3]
	v_mov_b64_e32 v[50:51], v[2:3]
	v_mov_b64_e32 v[52:53], v[2:3]
	v_mov_b64_e32 v[54:55], v[2:3]
	v_mov_b64_e32 v[56:57], v[2:3]
	v_mov_b64_e32 v[58:59], v[2:3]
	v_mov_b64_e32 v[60:61], v[2:3]
	v_mov_b64_e32 v[62:63], v[2:3]
	v_mov_b64_e32 v[64:65], v[2:3]
	v_mov_b64_e32 v[66:67], v[2:3]
	v_mov_b64_e32 v[68:69], v[2:3]
	v_mov_b64_e32 v[70:71], v[2:3]
	v_mov_b64_e32 v[72:73], v[2:3]
	v_mov_b64_e32 v[74:75], v[2:3]
	v_mov_b64_e32 v[76:77], v[2:3]
	v_mov_b64_e32 v[78:79], v[2:3]
	v_mov_b64_e32 v[80:81], v[2:3]
	v_mov_b64_e32 v[82:83], v[2:3]
	v_mov_b64_e32 v[84:85], v[2:3]
	v_mov_b64_e32 v[86:87], v[2:3]
	v_mov_b64_e32 v[88:89], v[2:3]
	v_mov_b64_e32 v[90:91], v[2:3]
	v_mov_b64_e32 v[92:93], v[2:3]
	v_mov_b64_e32 v[94:95], v[2:3]
	v_mov_b64_e32 v[96:97], v[2:3]
	v_mov_b64_e32 v[98:99], v[2:3]
	v_mov_b64_e32 v[100:101], v[2:3]
	v_mov_b64_e32 v[102:103], v[2:3]
	v_mov_b64_e32 v[104:105], v[2:3]
	v_mov_b64_e32 v[106:107], v[2:3]
	v_mov_b64_e32 v[108:109], v[2:3]
	v_mov_b64_e32 v[110:111], v[2:3]
	v_mov_b64_e32 v[112:113], v[2:3]
	v_mov_b64_e32 v[114:115], v[2:3]
	v_mov_b64_e32 v[116:117], v[2:3]
	v_mov_b64_e32 v[118:119], v[2:3]
	v_mov_b64_e32 v[120:121], v[2:3]
	v_mov_b64_e32 v[122:123], v[2:3]
	v_mov_b64_e32 v[124:125], v[2:3]
	v_mov_b64_e32 v[126:127], v[2:3]
	v_mov_b64_e32 v[128:129], v[2:3]
	s_branch .LBB0_974

; template <int MODE  , class Epi, class Sched>
; __device__ __forceinline__ void gemm_phase(LAS unsigned char* lds, const GemmDesc g, const Sched& S, const Epi& E) {
;     ...
;         if (zero) {
; #pragma unroll
;             for (int a = 0; a < 2; ++a)
; #pragma unroll
;                 for (int b = 0; b < 2; ++b)
; #pragma unroll
;                     for (int m = 0; m < 4; ++m)
; #pragma unroll
;                         for (int n = 0; n < 2; ++n) acc[a][b][m][n] = (f32x4){0.f, 0.f, 0.f, 0.f};
.LBB0_1016:
	s_add_u32 s85, s4, 0x100
	v_mov_b32_e32 v2, 0
	s_addc_u32 s86, s5, 0
	s_mov_b32 s87, -2
	v_mov_b32_e32 v3, v2
	v_mov_b64_e32 v[4:5], v[2:3]
	v_mov_b64_e32 v[6:7], v[2:3]
	v_mov_b64_e32 v[8:9], v[2:3]
	v_mov_b64_e32 v[18:19], v[2:3]
	v_mov_b64_e32 v[20:21], v[2:3]
	v_mov_b64_e32 v[22:23], v[2:3]
	v_mov_b64_e32 v[24:25], v[2:3]
	v_mov_b64_e32 v[34:35], v[2:3]
	v_mov_b64_e32 v[36:37], v[2:3]
	v_mov_b64_e32 v[38:39], v[2:3]
	v_mov_b64_e32 v[40:41], v[2:3]
	v_mov_b64_e32 v[50:51], v[2:3]
	v_mov_b64_e32 v[52:53], v[2:3]
	v_mov_b64_e32 v[54:55], v[2:3]
	v_mov_b64_e32 v[56:57], v[2:3]
	v_mov_b64_e32 v[10:11], v[2:3]
	v_mov_b64_e32 v[12:13], v[2:3]
	v_mov_b64_e32 v[14:15], v[2:3]
	v_mov_b64_e32 v[16:17], v[2:3]
	v_mov_b64_e32 v[26:27], v[2:3]
	v_mov_b64_e32 v[28:29], v[2:3]
	v_mov_b64_e32 v[30:31], v[2:3]
	v_mov_b64_e32 v[32:33], v[2:3]
	v_mov_b64_e32 v[42:43], v[2:3]
	v_mov_b64_e32 v[44:45], v[2:3]
	v_mov_b64_e32 v[46:47], v[2:3]
	v_mov_b64_e32 v[48:49], v[2:3]
	v_mov_b64_e32 v[58:59], v[2:3]
	v_mov_b64_e32 v[60:61], v[2:3]
	v_mov_b64_e32 v[62:63], v[2:3]
	v_mov_b64_e32 v[64:65], v[2:3]
	v_mov_b64_e32 v[66:67], v[2:3]
	v_mov_b64_e32 v[68:69], v[2:3]
	v_mov_b64_e32 v[70:71], v[2:3]
	v_mov_b64_e32 v[72:73], v[2:3]
	v_mov_b64_e32 v[82:83], v[2:3]
	v_mov_b64_e32 v[84:85], v[2:3]
	v_mov_b64_e32 v[86:87], v[2:3]
	v_mov_b64_e32 v[88:89], v[2:3]
	v_mov_b64_e32 v[98:99], v[2:3]
	v_mov_b64_e32 v[100:101], v[2:3]
	v_mov_b64_e32 v[102:103], v[2:3]
	v_mov_b64_e32 v[104:105], v[2:3]
	v_mov_b64_e32 v[114:115], v[2:3]
	v_mov_b64_e32 v[116:117], v[2:3]
	v_mov_b64_e32 v[118:119], v[2:3]
	v_mov_b64_e32 v[120:121], v[2:3]
	v_mov_b64_e32 v[74:75], v[2:3]
	v_mov_b64_e32 v[76:77], v[2:3]
	v_mov_b64_e32 v[78:79], v[2:3]
	v_mov_b64_e32 v[80:81], v[2:3]
	v_mov_b64_e32 v[90:91], v[2:3]
	v_mov_b64_e32 v[92:93], v[2:3]
	v_mov_b64_e32 v[94:95], v[2:3]
	v_mov_b64_e32 v[96:97], v[2:3]
	v_mov_b64_e32 v[106:107], v[2:3]
	v_mov_b64_e32 v[108:109], v[2:3]
	v_mov_b64_e32 v[110:111], v[2:3]
	v_mov_b64_e32 v[112:113], v[2:3]
	v_mov_b64_e32 v[122:123], v[2:3]
	v_mov_b64_e32 v[124:125], v[2:3]
	v_mov_b64_e32 v[126:127], v[2:3]
	v_mov_b64_e32 v[128:129], v[2:3]

; __global__ void __launch_bounds__(NTHREADS, 2) fwd_megakernel(Params p) {
	.amdhsa_kernel _Z14fwd_megakernel6Params
		.amdhsa_group_segment_fixed_size 0
		.amdhsa_private_segment_fixed_size 0
		.amdhsa_kernarg_size 384
		.amdhsa_user_sgpr_count 2
		.amdhsa_user_sgpr_dispatch_ptr 0
		.amdhsa_user_sgpr_queue_ptr 0
		.amdhsa_user_sgpr_kernarg_segment_ptr 1
		.amdhsa_user_sgpr_dispatch_id 0
		.amdhsa_user_sgpr_kernarg_preload_length 0
		.amdhsa_user_sgpr_kernarg_preload_offset 0
		.amdhsa_user_sgpr_private_segment_size 0
		.amdhsa_uses_dynamic_stack 0
		.amdhsa_enable_private_segment 0
		.amdhsa_system_sgpr_workgroup_id_x 1
		.amdhsa_system_sgpr_workgroup_id_y 0
		.amdhsa_system_sgpr_workgroup_id_z 0
		.amdhsa_system_sgpr_workgroup_info 0
		.amdhsa_system_vgpr_workitem_id 0
		.amdhsa_next_free_vgpr 256
		.amdhsa_next_free_sgpr 100
		.amdhsa_accum_offset 256
		.amdhsa_reserve_vcc 1
		.amdhsa_float_round_mode_32 0
		.amdhsa_float_round_mode_16_64 0
		.amdhsa_float_denorm_mode_32 3
		.amdhsa_float_denorm_mode_16_64 3
		.amdhsa_dx10_clamp 1
		.amdhsa_ieee_mode 1
		.amdhsa_fp16_overflow 0
		.amdhsa_tg_split 0
		.amdhsa_exception_fp_ieee_invalid_op 0
		.amdhsa_exception_fp_denorm_src 0
		.amdhsa_exception_fp_ieee_div_zero 0
		.amdhsa_exception_fp_ieee_overflow 0
		.amdhsa_exception_fp_ieee_underflow 0
		.amdhsa_exception_fp_ieee_inexact 0
		.amdhsa_exception_int_div_zero 0
	.end_amdhsa_kernel

; __global__ void __launch_bounds__(NTHREADS, 2) fwd_megakernel(Params p) {
.Lfunc_end0:
	.size	_Z14fwd_megakernel6Params, .Lfunc_end0-_Z14fwd_megakernel6Params
	.set _Z14fwd_megakernel6Params.num_vgpr, 256
	.set _Z14fwd_megakernel6Params.num_agpr, 0
	.set _Z14fwd_megakernel6Params.numbered_sgpr, 100
	.set _Z14fwd_megakernel6Params.num_named_barrier, 0
	.set _Z14fwd_megakernel6Params.private_seg_size, 0
	.set _Z14fwd_megakernel6Params.uses_vcc, 1
	.set _Z14fwd_megakernel6Params.uses_flat_scratch, 0
	.set _Z14fwd_megakernel6Params.has_dyn_sized_stack, 0
	.set _Z14fwd_megakernel6Params.has_recursion, 0
	.set _Z14fwd_megakernel6Params.has_indirect_call, 0

; __global__ void __launch_bounds__(NTHREADS, 2) fwd_megakernel(Params p) {
amdhsa.kernels:
  - .agpr_count:     0
    .args:
      - .offset:         0
        .size:           128
        .value_kind:     by_value
      - .offset:         128
        .size:           4
        .value_kind:     hidden_block_count_x
      - .offset:         132
        .size:           4
        .value_kind:     hidden_block_count_y
      - .offset:         136
        .size:           4
        .value_kind:     hidden_block_count_z
      - .offset:         140
        .size:           2
        .value_kind:     hidden_group_size_x
      - .offset:         142
        .size:           2
        .value_kind:     hidden_group_size_y
      - .offset:         144
        .size:           2
        .value_kind:     hidden_group_size_z
      - .offset:         146
        .size:           2
        .value_kind:     hidden_remainder_x
      - .offset:         148
        .size:           2
        .value_kind:     hidden_remainder_y
      - .offset:         150
        .size:           2
        .value_kind:     hidden_remainder_z
      - .offset:         168
        .size:           8
        .value_kind:     hidden_global_offset_x
      - .offset:         176
        .size:           8
        .value_kind:     hidden_global_offset_y
      - .offset:         184
        .size:           8
        .value_kind:     hidden_global_offset_z
      - .offset:         192
        .size:           2
        .value_kind:     hidden_grid_dims
      - .offset:         248
        .size:           4
        .value_kind:     hidden_dynamic_lds_size
    .group_segment_fixed_size: 0
    .kernarg_segment_align: 8
    .kernarg_segment_size: 384
    .language:       OpenCL C
    .language_version:
      - 2
      - 0
    .max_flat_workgroup_size: 512
    .name:           _Z14fwd_megakernel6Params
    .private_segment_fixed_size: 0
    .sgpr_count:     106
    .sgpr_spill_count: 8
    .symbol:         _Z14fwd_megakernel6Params.kd
    .uniform_work_group_size: 1
    .uses_dynamic_stack: false
    .vgpr_count:     256
    .vgpr_spill_count: 0
    .wavefront_size: 64
